# GEMM tile loops: first K iteration peeled with C=0 on each accumulator's first MFMA, accumulator zero-init removed (6 of 7 loops)
# baseline (speedup 1.0000x reference)
.LBB0_218:
	s_lshl_b32 s16, s42, 8
	s_ashr_i32 s17, s16, 31
	s_lshl_b64 s[16:17], s[16:17], 11
	s_add_u32 s16, s80, s16
	s_addc_u32 s17, s81, s17
	s_and_b64 s[22:23], s[2:3], exec
	s_cselect_b32 s44, s17, s27
	s_cselect_b32 s45, s16, s26
	s_lshl_b32 s22, s41, 8
	s_ashr_i32 s23, s22, 31
	s_lshl_b64 s[22:23], s[22:23], 11
	s_add_u32 s22, s29, s22
	s_addc_u32 s23, s30, s23
	s_and_b64 s[24:25], s[2:3], exec
	s_cselect_b32 s46, s23, s5
	s_cselect_b32 s47, s22, s4
	s_add_u32 s48, s4, 0x100
	s_addc_u32 s49, s5, 0
	s_add_u32 s4, s26, 0x40080
	s_addc_u32 s5, s27, 0
	s_mov_b32 s50, -2
	s_waitcnt vmcnt(0)
	s_add_u32 s24, s4, 0xfffc0080
	s_addc_u32 s25, s5, -1
	s_add_i32 s51, 0, 0x10000
	s_cmp_eq_u32 s50, 12
	s_cselect_b32 s27, s44, s25
	s_cselect_b32 s26, s45, s24
	s_cselect_b32 s25, s46, s49
	s_cselect_b32 s24, s47, s48
	s_add_i32 s54, 0, 0x14000
	v_add_u32_e32 v162, s51, v208
	v_add_u32_e32 v178, s54, v208
	ds_read_b128 v[130:133], v162
	ds_read_b128 v[134:137], v162 offset:1024
	ds_read_b128 v[158:161], v162 offset:2048
	ds_read_b128 v[162:165], v162 offset:3072
	ds_read_b128 v[166:169], v178
	ds_read_b128 v[170:173], v178 offset:1024
	ds_read_b128 v[174:177], v178 offset:2048
	ds_read_b128 v[178:181], v178 offset:3072
	v_lshl_add_u64 v[226:227], s[4:5], 0, v[156:157]
	s_add_i32 m0, s31, 0xc000
	ds_read_b128 v[182:185], v209
	ds_read_b128 v[186:189], v209 offset:1024
	ds_read_b128 v[194:197], v209 offset:2048
	ds_read_b128 v[198:201], v209 offset:3072
	ds_read_b128 v[210:213], v209 offset:4096
	ds_read_b128 v[214:217], v209 offset:5120
	ds_read_b128 v[218:221], v209 offset:6144
	ds_read_b128 v[222:225], v209 offset:7168
	global_load_lds_dwordx4 v[226:227], off
	v_lshl_add_u64 v[226:227], s[4:5], 0, v[154:155]
	s_add_i32 m0, s31, 0xe000
	s_nop 0
	global_load_lds_dwordx4 v[226:227], off
	s_waitcnt vmcnt(8)
	s_waitcnt lgkmcnt(0)
	s_barrier
	s_setprio 1
	s_waitcnt lgkmcnt(0)
	v_mfma_f32_16x16x32_bf16 v[126:129], v[130:133], v[182:185], 0
	v_mfma_f32_16x16x32_bf16 v[122:125], v[158:161], v[182:185], 0
	v_mfma_f32_16x16x32_bf16 v[110:113], v[130:133], v[194:197], 0
	v_mfma_f32_16x16x32_bf16 v[106:109], v[158:161], v[194:197], 0
	v_mfma_f32_16x16x32_bf16 v[94:97], v[130:133], v[210:213], 0
	v_mfma_f32_16x16x32_bf16 v[90:93], v[158:161], v[210:213], 0
	v_mfma_f32_16x16x32_bf16 v[78:81], v[130:133], v[218:221], 0
	v_mfma_f32_16x16x32_bf16 v[74:77], v[158:161], v[218:221], 0
	v_mfma_f32_16x16x32_bf16 v[126:129], v[134:137], v[186:189], v[126:129]
	v_mfma_f32_16x16x32_bf16 v[122:125], v[162:165], v[186:189], v[122:125]
	v_mfma_f32_16x16x32_bf16 v[110:113], v[134:137], v[198:201], v[110:113]
	v_mfma_f32_16x16x32_bf16 v[106:109], v[162:165], v[198:201], v[106:109]
	v_mfma_f32_16x16x32_bf16 v[94:97], v[134:137], v[214:217], v[94:97]
	v_mfma_f32_16x16x32_bf16 v[90:93], v[162:165], v[214:217], v[90:93]
	v_mfma_f32_16x16x32_bf16 v[78:81], v[134:137], v[222:225], v[78:81]
	v_mfma_f32_16x16x32_bf16 v[74:77], v[162:165], v[222:225], v[74:77]
	s_setprio 0
	s_setprio 1
	v_mfma_f32_16x16x32_bf16 v[118:121], v[166:169], v[182:185], 0
	v_mfma_f32_16x16x32_bf16 v[114:117], v[174:177], v[182:185], 0
	v_mfma_f32_16x16x32_bf16 v[102:105], v[166:169], v[194:197], 0
	v_mfma_f32_16x16x32_bf16 v[98:101], v[174:177], v[194:197], 0
	v_mfma_f32_16x16x32_bf16 v[86:89], v[166:169], v[210:213], 0
	v_mfma_f32_16x16x32_bf16 v[82:85], v[174:177], v[210:213], 0
	v_mfma_f32_16x16x32_bf16 v[70:73], v[166:169], v[218:221], 0
	v_mfma_f32_16x16x32_bf16 v[66:69], v[174:177], v[218:221], 0
	v_mfma_f32_16x16x32_bf16 v[118:121], v[170:173], v[186:189], v[118:121]
	v_mfma_f32_16x16x32_bf16 v[114:117], v[178:181], v[186:189], v[114:117]
	v_mfma_f32_16x16x32_bf16 v[102:105], v[170:173], v[198:201], v[102:105]
	v_mfma_f32_16x16x32_bf16 v[98:101], v[178:181], v[198:201], v[98:101]
	v_mfma_f32_16x16x32_bf16 v[86:89], v[170:173], v[214:217], v[86:89]
	v_mfma_f32_16x16x32_bf16 v[82:85], v[178:181], v[214:217], v[82:85]
	v_mfma_f32_16x16x32_bf16 v[70:73], v[170:173], v[222:225], v[70:73]
	v_mfma_f32_16x16x32_bf16 v[66:69], v[178:181], v[222:225], v[66:69]
	s_setprio 0
	s_barrier
	s_add_i32 s51, s51, s28
	v_lshl_add_u64 v[226:227], s[24:25], 0, v[140:141]
	s_mov_b32 m0, s51
	ds_read_b128 v[182:185], v209 offset:16384
	ds_read_b128 v[186:189], v209 offset:17408
	ds_read_b128 v[194:197], v209 offset:18432
	ds_read_b128 v[198:201], v209 offset:19456
	ds_read_b128 v[210:213], v209 offset:20480
	ds_read_b128 v[214:217], v209 offset:21504
	ds_read_b128 v[218:221], v209 offset:22528
	ds_read_b128 v[222:225], v209 offset:23552
	global_load_lds_dwordx4 v[226:227], off
	s_add_i32 m0, s51, 0x2000
	s_add_u32 s52, s24, 0x40000
	v_lshl_add_u64 v[228:229], s[24:25], 0, v[144:145]
	s_addc_u32 s53, s25, 0
	s_add_i32 s51, s54, s28
	global_load_lds_dwordx4 v[228:229], off
	v_lshl_add_u64 v[230:231], s[52:53], 0, v[140:141]
	s_mov_b32 m0, s51
	v_lshl_add_u64 v[244:245], s[26:27], 0, v[142:143]
	global_load_lds_dwordx4 v[230:231], off
	v_lshl_add_u64 v[230:231], s[52:53], 0, v[144:145]
	s_add_i32 m0, s51, 0x2000
	s_nop 0
	global_load_lds_dwordx4 v[230:231], off
	v_lshl_add_u64 v[230:231], s[26:27], 0, v[138:139]
	s_mov_b32 m0, s31
	s_nop 0
	global_load_lds_dwordx4 v[230:231], off
	s_mov_b32 m0, s34
	s_nop 0
	global_load_lds_dwordx4 v[244:245], off
	s_waitcnt vmcnt(8)
	s_waitcnt lgkmcnt(0)
	s_barrier
	s_setprio 1
	s_waitcnt lgkmcnt(0)
	v_mfma_f32_16x16x32_bf16 v[62:65], v[130:133], v[182:185], 0
	v_mfma_f32_16x16x32_bf16 v[58:61], v[158:161], v[182:185], 0
	v_mfma_f32_16x16x32_bf16 v[46:49], v[130:133], v[194:197], 0
	v_mfma_f32_16x16x32_bf16 v[42:45], v[158:161], v[194:197], 0
	v_mfma_f32_16x16x32_bf16 v[30:33], v[130:133], v[210:213], 0
	v_mfma_f32_16x16x32_bf16 v[26:29], v[158:161], v[210:213], 0
	v_mfma_f32_16x16x32_bf16 v[14:17], v[130:133], v[218:221], 0
	v_mfma_f32_16x16x32_bf16 v[10:13], v[158:161], v[218:221], 0
	v_mfma_f32_16x16x32_bf16 v[62:65], v[134:137], v[186:189], v[62:65]
	v_mfma_f32_16x16x32_bf16 v[58:61], v[162:165], v[186:189], v[58:61]
	v_mfma_f32_16x16x32_bf16 v[46:49], v[134:137], v[198:201], v[46:49]
	v_mfma_f32_16x16x32_bf16 v[42:45], v[162:165], v[198:201], v[42:45]
	v_mfma_f32_16x16x32_bf16 v[30:33], v[134:137], v[214:217], v[30:33]
	v_mfma_f32_16x16x32_bf16 v[26:29], v[162:165], v[214:217], v[26:29]
	v_mfma_f32_16x16x32_bf16 v[14:17], v[134:137], v[222:225], v[14:17]
	v_mfma_f32_16x16x32_bf16 v[10:13], v[162:165], v[222:225], v[10:13]
	s_setprio 0
	s_setprio 1
	v_mfma_f32_16x16x32_bf16 v[54:57], v[166:169], v[182:185], 0
	v_mfma_f32_16x16x32_bf16 v[50:53], v[174:177], v[182:185], 0
	v_mfma_f32_16x16x32_bf16 v[38:41], v[166:169], v[194:197], 0
	v_mfma_f32_16x16x32_bf16 v[34:37], v[174:177], v[194:197], 0
	v_mfma_f32_16x16x32_bf16 v[22:25], v[166:169], v[210:213], 0
	v_mfma_f32_16x16x32_bf16 v[18:21], v[174:177], v[210:213], 0
	v_mfma_f32_16x16x32_bf16 v[6:9], v[166:169], v[218:221], 0
	v_mfma_f32_16x16x32_bf16 v[2:5], v[174:177], v[218:221], 0
	v_mfma_f32_16x16x32_bf16 v[54:57], v[170:173], v[186:189], v[54:57]
	v_mfma_f32_16x16x32_bf16 v[50:53], v[178:181], v[186:189], v[50:53]
	v_mfma_f32_16x16x32_bf16 v[38:41], v[170:173], v[198:201], v[38:41]
	v_mfma_f32_16x16x32_bf16 v[34:37], v[178:181], v[198:201], v[34:37]
	v_mfma_f32_16x16x32_bf16 v[22:25], v[170:173], v[214:217], v[22:25]
	v_mfma_f32_16x16x32_bf16 v[18:21], v[178:181], v[214:217], v[18:21]
	v_mfma_f32_16x16x32_bf16 v[6:9], v[170:173], v[222:225], v[6:9]
	v_mfma_f32_16x16x32_bf16 v[2:5], v[178:181], v[222:225], v[2:5]
	s_setprio 0
	s_barrier
	s_add_i32 s51, 0, 0x18000
	s_add_i32 s52, 0, 0x1c000
	v_add_u32_e32 v162, s51, v208
	v_add_u32_e32 v178, s52, v208
	ds_read_b128 v[130:133], v162
	ds_read_b128 v[134:137], v162 offset:1024
	ds_read_b128 v[158:161], v162 offset:2048
	ds_read_b128 v[162:165], v162 offset:3072
	ds_read_b128 v[166:169], v178
	ds_read_b128 v[170:173], v178 offset:1024
	ds_read_b128 v[174:177], v178 offset:2048
	ds_read_b128 v[178:181], v178 offset:3072
	s_add_u32 s26, s26, 0x40000
	s_addc_u32 s27, s27, 0
	s_mov_b32 m0, s35
	v_lshl_add_u64 v[246:247], s[26:27], 0, v[138:139]
	ds_read_b128 v[182:185], v209 offset:32768
	ds_read_b128 v[186:189], v209 offset:33792
	ds_read_b128 v[194:197], v209 offset:34816
	ds_read_b128 v[198:201], v209 offset:35840
	ds_read_b128 v[210:213], v209 offset:36864
	ds_read_b128 v[214:217], v209 offset:37888
	ds_read_b128 v[218:221], v209 offset:38912
	ds_read_b128 v[222:225], v209 offset:39936
	global_load_lds_dwordx4 v[246:247], off
	v_lshl_add_u64 v[246:247], s[26:27], 0, v[142:143]
	s_mov_b32 m0, s36
	s_nop 0
	global_load_lds_dwordx4 v[246:247], off
	s_waitcnt vmcnt(8)
	s_waitcnt lgkmcnt(0)
	s_barrier
	s_setprio 1
	s_waitcnt lgkmcnt(0)
	v_mfma_f32_16x16x32_bf16 v[126:129], v[130:133], v[182:185], v[126:129]
	v_mfma_f32_16x16x32_bf16 v[122:125], v[158:161], v[182:185], v[122:125]
	v_mfma_f32_16x16x32_bf16 v[110:113], v[130:133], v[194:197], v[110:113]
	v_mfma_f32_16x16x32_bf16 v[106:109], v[158:161], v[194:197], v[106:109]
	v_mfma_f32_16x16x32_bf16 v[94:97], v[130:133], v[210:213], v[94:97]
	v_mfma_f32_16x16x32_bf16 v[90:93], v[158:161], v[210:213], v[90:93]
	v_mfma_f32_16x16x32_bf16 v[78:81], v[130:133], v[218:221], v[78:81]
	v_mfma_f32_16x16x32_bf16 v[74:77], v[158:161], v[218:221], v[74:77]
	v_mfma_f32_16x16x32_bf16 v[126:129], v[134:137], v[186:189], v[126:129]
	v_mfma_f32_16x16x32_bf16 v[122:125], v[162:165], v[186:189], v[122:125]
	v_mfma_f32_16x16x32_bf16 v[110:113], v[134:137], v[198:201], v[110:113]
	v_mfma_f32_16x16x32_bf16 v[106:109], v[162:165], v[198:201], v[106:109]
	v_mfma_f32_16x16x32_bf16 v[94:97], v[134:137], v[214:217], v[94:97]
	v_mfma_f32_16x16x32_bf16 v[90:93], v[162:165], v[214:217], v[90:93]
	v_mfma_f32_16x16x32_bf16 v[78:81], v[134:137], v[222:225], v[78:81]
	v_mfma_f32_16x16x32_bf16 v[74:77], v[162:165], v[222:225], v[74:77]
	s_setprio 0
	s_setprio 1
	v_mfma_f32_16x16x32_bf16 v[118:121], v[166:169], v[182:185], v[118:121]
	v_mfma_f32_16x16x32_bf16 v[114:117], v[174:177], v[182:185], v[114:117]
	v_mfma_f32_16x16x32_bf16 v[102:105], v[166:169], v[194:197], v[102:105]
	v_mfma_f32_16x16x32_bf16 v[98:101], v[174:177], v[194:197], v[98:101]
	v_mfma_f32_16x16x32_bf16 v[86:89], v[166:169], v[210:213], v[86:89]
	v_mfma_f32_16x16x32_bf16 v[82:85], v[174:177], v[210:213], v[82:85]
	v_mfma_f32_16x16x32_bf16 v[70:73], v[166:169], v[218:221], v[70:73]
	v_mfma_f32_16x16x32_bf16 v[66:69], v[174:177], v[218:221], v[66:69]
	v_mfma_f32_16x16x32_bf16 v[118:121], v[170:173], v[186:189], v[118:121]
	v_mfma_f32_16x16x32_bf16 v[114:117], v[178:181], v[186:189], v[114:117]
	v_mfma_f32_16x16x32_bf16 v[102:105], v[170:173], v[198:201], v[102:105]
	v_mfma_f32_16x16x32_bf16 v[98:101], v[178:181], v[198:201], v[98:101]
	v_mfma_f32_16x16x32_bf16 v[86:89], v[170:173], v[214:217], v[86:89]
	v_mfma_f32_16x16x32_bf16 v[82:85], v[178:181], v[214:217], v[82:85]
	v_mfma_f32_16x16x32_bf16 v[70:73], v[170:173], v[222:225], v[70:73]
	v_mfma_f32_16x16x32_bf16 v[66:69], v[178:181], v[222:225], v[66:69]
	s_setprio 0
	s_barrier
	s_add_i32 s26, s51, s28
	v_lshl_add_u64 v[226:227], v[226:227], 0, s[90:91]
	s_mov_b32 m0, s26
	ds_read_b128 v[182:185], v209 offset:49152
	ds_read_b128 v[186:189], v209 offset:50176
	ds_read_b128 v[194:197], v209 offset:51200
	ds_read_b128 v[198:201], v209 offset:52224
	ds_read_b128 v[210:213], v209 offset:53248
	ds_read_b128 v[214:217], v209 offset:54272
	ds_read_b128 v[218:221], v209 offset:55296
	ds_read_b128 v[222:225], v209 offset:56320
	global_load_lds_dwordx4 v[226:227], off
	s_add_i32 m0, s26, 0x2000
	s_add_u32 s24, s24, 0x40080
	v_lshl_add_u64 v[226:227], v[228:229], 0, s[90:91]
	s_addc_u32 s25, s25, 0
	s_add_i32 s26, s52, s28
	global_load_lds_dwordx4 v[226:227], off
	v_lshl_add_u64 v[226:227], s[24:25], 0, v[140:141]
	s_mov_b32 m0, s26
	s_nop 0
	global_load_lds_dwordx4 v[226:227], off
	v_lshl_add_u64 v[226:227], s[24:25], 0, v[144:145]
	s_add_i32 m0, s26, 0x2000
	s_nop 0
	global_load_lds_dwordx4 v[226:227], off
	v_lshl_add_u64 v[226:227], v[230:231], 0, s[90:91]
	s_mov_b32 m0, s37
	s_nop 0
	global_load_lds_dwordx4 v[226:227], off
	v_lshl_add_u64 v[226:227], v[244:245], 0, s[90:91]
	s_mov_b32 m0, s38
	s_nop 0
	global_load_lds_dwordx4 v[226:227], off
	s_waitcnt vmcnt(8)
	s_waitcnt lgkmcnt(0)
	s_barrier
	s_setprio 1
	s_waitcnt lgkmcnt(0)
	v_mfma_f32_16x16x32_bf16 v[62:65], v[130:133], v[182:185], v[62:65]
	v_mfma_f32_16x16x32_bf16 v[58:61], v[158:161], v[182:185], v[58:61]
	v_mfma_f32_16x16x32_bf16 v[46:49], v[130:133], v[194:197], v[46:49]
	v_mfma_f32_16x16x32_bf16 v[42:45], v[158:161], v[194:197], v[42:45]
	v_mfma_f32_16x16x32_bf16 v[30:33], v[130:133], v[210:213], v[30:33]
	v_mfma_f32_16x16x32_bf16 v[26:29], v[158:161], v[210:213], v[26:29]
	v_mfma_f32_16x16x32_bf16 v[14:17], v[130:133], v[218:221], v[14:17]
	v_mfma_f32_16x16x32_bf16 v[10:13], v[158:161], v[218:221], v[10:13]
	v_mfma_f32_16x16x32_bf16 v[62:65], v[134:137], v[186:189], v[62:65]
	v_mfma_f32_16x16x32_bf16 v[58:61], v[162:165], v[186:189], v[58:61]
	v_mfma_f32_16x16x32_bf16 v[46:49], v[134:137], v[198:201], v[46:49]
	v_mfma_f32_16x16x32_bf16 v[42:45], v[162:165], v[198:201], v[42:45]
	v_mfma_f32_16x16x32_bf16 v[30:33], v[134:137], v[214:217], v[30:33]
	v_mfma_f32_16x16x32_bf16 v[26:29], v[162:165], v[214:217], v[26:29]
	v_mfma_f32_16x16x32_bf16 v[14:17], v[134:137], v[222:225], v[14:17]
	v_mfma_f32_16x16x32_bf16 v[10:13], v[162:165], v[222:225], v[10:13]
	s_setprio 0
	s_setprio 1
	v_mfma_f32_16x16x32_bf16 v[54:57], v[166:169], v[182:185], v[54:57]
	v_mfma_f32_16x16x32_bf16 v[50:53], v[174:177], v[182:185], v[50:53]
	v_mfma_f32_16x16x32_bf16 v[38:41], v[166:169], v[194:197], v[38:41]
	v_mfma_f32_16x16x32_bf16 v[34:37], v[174:177], v[194:197], v[34:37]
	v_mfma_f32_16x16x32_bf16 v[22:25], v[166:169], v[210:213], v[22:25]
	v_mfma_f32_16x16x32_bf16 v[18:21], v[174:177], v[210:213], v[18:21]
	v_mfma_f32_16x16x32_bf16 v[6:9], v[166:169], v[218:221], v[6:9]
	v_mfma_f32_16x16x32_bf16 v[2:5], v[174:177], v[218:221], v[2:5]
	v_mfma_f32_16x16x32_bf16 v[54:57], v[170:173], v[186:189], v[54:57]
	v_mfma_f32_16x16x32_bf16 v[50:53], v[178:181], v[186:189], v[50:53]
	v_mfma_f32_16x16x32_bf16 v[38:41], v[170:173], v[198:201], v[38:41]
	v_mfma_f32_16x16x32_bf16 v[34:37], v[178:181], v[198:201], v[34:37]
	v_mfma_f32_16x16x32_bf16 v[22:25], v[170:173], v[214:217], v[22:25]
	v_mfma_f32_16x16x32_bf16 v[18:21], v[178:181], v[214:217], v[18:21]
	v_mfma_f32_16x16x32_bf16 v[6:9], v[170:173], v[222:225], v[6:9]
	v_mfma_f32_16x16x32_bf16 v[2:5], v[178:181], v[222:225], v[2:5]
	s_setprio 0
	s_barrier
	s_add_i32 s50, s50, 2
	s_add_u32 s48, s48, 0x100
	s_addc_u32 s49, s49, 0
	s_add_u32 s4, s4, 0x100
	s_addc_u32 s5, s5, 0

.LBB0_290:
	s_lshl_b32 s12, s39, 8
	s_ashr_i32 s13, s12, 31
	s_lshl_b64 s[12:13], s[12:13], 11
	s_add_u32 s12, s27, s12
	s_addc_u32 s13, s28, s13
	s_and_b64 s[14:15], s[2:3], exec
	s_cselect_b32 s42, s13, s23
	s_cselect_b32 s43, s12, s22
	s_lshl_b32 s14, s38, 8
	s_ashr_i32 s15, s14, 31
	s_lshl_b64 s[14:15], s[14:15], 11
	s_add_u32 s14, s80, s14
	s_addc_u32 s15, s81, s15
	s_and_b64 s[24:25], s[2:3], exec
	s_cselect_b32 s44, s15, s17
	s_cselect_b32 s45, s14, s16
	s_add_u32 s46, s16, 0x100
	s_addc_u32 s47, s17, 0
	s_add_u32 s16, s22, 0x40080
	s_addc_u32 s17, s23, 0
	s_mov_b32 s48, -2
	s_add_u32 s22, s16, 0xfffc0080
	s_addc_u32 s23, s17, -1
	s_add_i32 s49, 0, 0x10000
	s_cmp_eq_u32 s48, 12
	s_cselect_b32 s25, s42, s23
	s_cselect_b32 s24, s43, s22
	v_add_u32_e32 v152, s49, v154
	s_cselect_b32 s23, s44, s47
	s_cselect_b32 s22, s45, s46
	s_add_i32 s52, 0, 0x14000
	ds_read_b128 v[134:137], v152
	ds_read_b128 v[148:151], v152 offset:1024
	ds_read_b128 v[158:161], v152 offset:2048
	ds_read_b128 v[162:165], v152 offset:3072
	v_add_u32_e32 v152, s52, v154
	ds_read_b128 v[166:169], v152
	ds_read_b128 v[170:173], v152 offset:1024
	ds_read_b128 v[174:177], v152 offset:2048
	ds_read_b128 v[178:181], v152 offset:3072
	v_lshl_add_u64 v[152:153], s[16:17], 0, v[132:133]
	s_add_i32 m0, s30, 0xc000
	ds_read_b128 v[182:185], v156
	ds_read_b128 v[186:189], v156 offset:1024
	ds_read_b128 v[190:193], v156 offset:2048
	ds_read_b128 v[194:197], v156 offset:3072
	ds_read_b128 v[198:201], v156 offset:4096
	ds_read_b128 v[202:205], v156 offset:5120
	ds_read_b128 v[206:209], v156 offset:6144
	ds_read_b128 v[210:213], v156 offset:7168
	global_load_lds_dwordx4 v[152:153], off
	v_lshl_add_u64 v[152:153], s[16:17], 0, v[130:131]
	s_add_i32 m0, s30, 0xe000
	s_nop 0
	global_load_lds_dwordx4 v[152:153], off
	s_waitcnt vmcnt(8)
	s_waitcnt lgkmcnt(0)
	s_barrier
	s_setprio 1
	s_waitcnt lgkmcnt(0)
	v_mfma_f32_16x16x32_bf16 v[126:129], v[134:137], v[182:185], 0
	v_mfma_f32_16x16x32_bf16 v[122:125], v[158:161], v[182:185], 0
	v_mfma_f32_16x16x32_bf16 v[118:121], v[134:137], v[190:193], 0
	v_mfma_f32_16x16x32_bf16 v[114:117], v[158:161], v[190:193], 0
	v_mfma_f32_16x16x32_bf16 v[110:113], v[134:137], v[198:201], 0
	v_mfma_f32_16x16x32_bf16 v[106:109], v[158:161], v[198:201], 0
	v_mfma_f32_16x16x32_bf16 v[102:105], v[134:137], v[206:209], 0
	v_mfma_f32_16x16x32_bf16 v[98:101], v[158:161], v[206:209], 0
	v_mfma_f32_16x16x32_bf16 v[126:129], v[148:151], v[186:189], v[126:129]
	v_mfma_f32_16x16x32_bf16 v[122:125], v[162:165], v[186:189], v[122:125]
	v_mfma_f32_16x16x32_bf16 v[118:121], v[148:151], v[194:197], v[118:121]
	v_mfma_f32_16x16x32_bf16 v[114:117], v[162:165], v[194:197], v[114:117]
	v_mfma_f32_16x16x32_bf16 v[110:113], v[148:151], v[202:205], v[110:113]
	v_mfma_f32_16x16x32_bf16 v[106:109], v[162:165], v[202:205], v[106:109]
	v_mfma_f32_16x16x32_bf16 v[102:105], v[148:151], v[210:213], v[102:105]
	v_mfma_f32_16x16x32_bf16 v[98:101], v[162:165], v[210:213], v[98:101]
	s_setprio 0
	s_setprio 1
	v_mfma_f32_16x16x32_bf16 v[70:73], v[166:169], v[182:185], 0
	v_mfma_f32_16x16x32_bf16 v[66:69], v[174:177], v[182:185], 0
	v_mfma_f32_16x16x32_bf16 v[54:57], v[166:169], v[190:193], 0
	v_mfma_f32_16x16x32_bf16 v[50:53], v[174:177], v[190:193], 0
	v_mfma_f32_16x16x32_bf16 v[46:49], v[166:169], v[198:201], 0
	v_mfma_f32_16x16x32_bf16 v[42:45], v[174:177], v[198:201], 0
	v_mfma_f32_16x16x32_bf16 v[38:41], v[166:169], v[206:209], 0
	v_mfma_f32_16x16x32_bf16 v[34:37], v[174:177], v[206:209], 0
	v_mfma_f32_16x16x32_bf16 v[70:73], v[170:173], v[186:189], v[70:73]
	v_mfma_f32_16x16x32_bf16 v[66:69], v[178:181], v[186:189], v[66:69]
	v_mfma_f32_16x16x32_bf16 v[54:57], v[170:173], v[194:197], v[54:57]
	v_mfma_f32_16x16x32_bf16 v[50:53], v[178:181], v[194:197], v[50:53]
	v_mfma_f32_16x16x32_bf16 v[46:49], v[170:173], v[202:205], v[46:49]
	v_mfma_f32_16x16x32_bf16 v[42:45], v[178:181], v[202:205], v[42:45]
	v_mfma_f32_16x16x32_bf16 v[38:41], v[170:173], v[210:213], v[38:41]
	v_mfma_f32_16x16x32_bf16 v[34:37], v[178:181], v[210:213], v[34:37]
	s_setprio 0
	s_barrier
	s_add_i32 s49, s49, s29
	v_lshl_add_u64 v[152:153], s[22:23], 0, v[140:141]
	s_mov_b32 m0, s49
	ds_read_b128 v[182:185], v156 offset:16384
	ds_read_b128 v[186:189], v156 offset:17408
	ds_read_b128 v[190:193], v156 offset:18432
	ds_read_b128 v[194:197], v156 offset:19456
	ds_read_b128 v[198:201], v156 offset:20480
	ds_read_b128 v[202:205], v156 offset:21504
	ds_read_b128 v[206:209], v156 offset:22528
	ds_read_b128 v[210:213], v156 offset:23552
	global_load_lds_dwordx4 v[152:153], off
	s_add_i32 m0, s49, 0x2000
	s_add_u32 s50, s22, 0x40000
	v_lshl_add_u64 v[214:215], s[22:23], 0, v[144:145]
	s_addc_u32 s51, s23, 0
	s_add_i32 s49, s52, s29
	global_load_lds_dwordx4 v[214:215], off
	v_lshl_add_u64 v[216:217], s[50:51], 0, v[140:141]
	s_mov_b32 m0, s49
	v_lshl_add_u64 v[218:219], s[24:25], 0, v[142:143]
	global_load_lds_dwordx4 v[216:217], off
	v_lshl_add_u64 v[216:217], s[50:51], 0, v[144:145]
	s_add_i32 m0, s49, 0x2000
	s_nop 0
	global_load_lds_dwordx4 v[216:217], off
	v_lshl_add_u64 v[216:217], s[24:25], 0, v[138:139]
	s_mov_b32 m0, s30
	s_nop 0
	global_load_lds_dwordx4 v[216:217], off
	s_mov_b32 m0, s31
	s_nop 0
	global_load_lds_dwordx4 v[218:219], off
	s_waitcnt vmcnt(8)
	s_waitcnt lgkmcnt(0)
	s_barrier
	s_setprio 1
	s_waitcnt lgkmcnt(0)
	v_mfma_f32_16x16x32_bf16 v[94:97], v[134:137], v[182:185], 0
	v_mfma_f32_16x16x32_bf16 v[90:93], v[158:161], v[182:185], 0
	v_mfma_f32_16x16x32_bf16 v[86:89], v[134:137], v[190:193], 0
	v_mfma_f32_16x16x32_bf16 v[82:85], v[158:161], v[190:193], 0
	v_mfma_f32_16x16x32_bf16 v[78:81], v[134:137], v[198:201], 0
	v_mfma_f32_16x16x32_bf16 v[74:77], v[158:161], v[198:201], 0
	v_mfma_f32_16x16x32_bf16 v[62:65], v[134:137], v[206:209], 0
	v_mfma_f32_16x16x32_bf16 v[58:61], v[158:161], v[206:209], 0
	v_mfma_f32_16x16x32_bf16 v[94:97], v[148:151], v[186:189], v[94:97]
	v_mfma_f32_16x16x32_bf16 v[90:93], v[162:165], v[186:189], v[90:93]
	v_mfma_f32_16x16x32_bf16 v[86:89], v[148:151], v[194:197], v[86:89]
	v_mfma_f32_16x16x32_bf16 v[82:85], v[162:165], v[194:197], v[82:85]
	v_mfma_f32_16x16x32_bf16 v[78:81], v[148:151], v[202:205], v[78:81]
	v_mfma_f32_16x16x32_bf16 v[74:77], v[162:165], v[202:205], v[74:77]
	v_mfma_f32_16x16x32_bf16 v[62:65], v[148:151], v[210:213], v[62:65]
	v_mfma_f32_16x16x32_bf16 v[58:61], v[162:165], v[210:213], v[58:61]
	s_setprio 0
	s_setprio 1
	v_mfma_f32_16x16x32_bf16 v[30:33], v[166:169], v[182:185], 0
	v_mfma_f32_16x16x32_bf16 v[26:29], v[174:177], v[182:185], 0
	v_mfma_f32_16x16x32_bf16 v[22:25], v[166:169], v[190:193], 0
	v_mfma_f32_16x16x32_bf16 v[18:21], v[174:177], v[190:193], 0
	v_mfma_f32_16x16x32_bf16 v[14:17], v[166:169], v[198:201], 0
	v_mfma_f32_16x16x32_bf16 v[10:13], v[174:177], v[198:201], 0
	v_mfma_f32_16x16x32_bf16 v[6:9], v[166:169], v[206:209], 0
	v_mfma_f32_16x16x32_bf16 v[2:5], v[174:177], v[206:209], 0
	v_mfma_f32_16x16x32_bf16 v[30:33], v[170:173], v[186:189], v[30:33]
	v_mfma_f32_16x16x32_bf16 v[26:29], v[178:181], v[186:189], v[26:29]
	v_mfma_f32_16x16x32_bf16 v[22:25], v[170:173], v[194:197], v[22:25]
	v_mfma_f32_16x16x32_bf16 v[18:21], v[178:181], v[194:197], v[18:21]
	v_mfma_f32_16x16x32_bf16 v[14:17], v[170:173], v[202:205], v[14:17]
	v_mfma_f32_16x16x32_bf16 v[10:13], v[178:181], v[202:205], v[10:13]
	v_mfma_f32_16x16x32_bf16 v[6:9], v[170:173], v[210:213], v[6:9]
	v_mfma_f32_16x16x32_bf16 v[2:5], v[178:181], v[210:213], v[2:5]
	s_setprio 0
	s_barrier
	s_add_i32 s49, 0, 0x18000
	v_add_u32_e32 v157, s49, v154
	s_add_i32 s50, 0, 0x1c000
	ds_read_b128 v[134:137], v157
	ds_read_b128 v[148:151], v157 offset:1024
	ds_read_b128 v[158:161], v157 offset:2048
	ds_read_b128 v[162:165], v157 offset:3072
	v_add_u32_e32 v157, s50, v154
	ds_read_b128 v[166:169], v157
	ds_read_b128 v[170:173], v157 offset:1024
	ds_read_b128 v[174:177], v157 offset:2048
	ds_read_b128 v[178:181], v157 offset:3072
	s_add_u32 s24, s24, 0x40000
	s_addc_u32 s25, s25, 0
	s_mov_b32 m0, s33
	v_lshl_add_u64 v[220:221], s[24:25], 0, v[138:139]
	ds_read_b128 v[182:185], v156 offset:32768
	ds_read_b128 v[186:189], v156 offset:33792
	ds_read_b128 v[190:193], v156 offset:34816
	ds_read_b128 v[194:197], v156 offset:35840
	ds_read_b128 v[198:201], v156 offset:36864
	ds_read_b128 v[202:205], v156 offset:37888
	ds_read_b128 v[206:209], v156 offset:38912
	ds_read_b128 v[210:213], v156 offset:39936
	global_load_lds_dwordx4 v[220:221], off
	v_lshl_add_u64 v[220:221], s[24:25], 0, v[142:143]
	s_mov_b32 m0, s34
	s_nop 0
	global_load_lds_dwordx4 v[220:221], off
	s_waitcnt vmcnt(8)
	s_waitcnt lgkmcnt(0)
	s_barrier
	s_setprio 1
	s_waitcnt lgkmcnt(0)
	v_mfma_f32_16x16x32_bf16 v[126:129], v[134:137], v[182:185], v[126:129]
	v_mfma_f32_16x16x32_bf16 v[122:125], v[158:161], v[182:185], v[122:125]
	v_mfma_f32_16x16x32_bf16 v[118:121], v[134:137], v[190:193], v[118:121]
	v_mfma_f32_16x16x32_bf16 v[114:117], v[158:161], v[190:193], v[114:117]
	v_mfma_f32_16x16x32_bf16 v[110:113], v[134:137], v[198:201], v[110:113]
	v_mfma_f32_16x16x32_bf16 v[106:109], v[158:161], v[198:201], v[106:109]
	v_mfma_f32_16x16x32_bf16 v[102:105], v[134:137], v[206:209], v[102:105]
	v_mfma_f32_16x16x32_bf16 v[98:101], v[158:161], v[206:209], v[98:101]
	v_mfma_f32_16x16x32_bf16 v[126:129], v[148:151], v[186:189], v[126:129]
	v_mfma_f32_16x16x32_bf16 v[122:125], v[162:165], v[186:189], v[122:125]
	v_mfma_f32_16x16x32_bf16 v[118:121], v[148:151], v[194:197], v[118:121]
	v_mfma_f32_16x16x32_bf16 v[114:117], v[162:165], v[194:197], v[114:117]
	v_mfma_f32_16x16x32_bf16 v[110:113], v[148:151], v[202:205], v[110:113]
	v_mfma_f32_16x16x32_bf16 v[106:109], v[162:165], v[202:205], v[106:109]
	v_mfma_f32_16x16x32_bf16 v[102:105], v[148:151], v[210:213], v[102:105]
	v_mfma_f32_16x16x32_bf16 v[98:101], v[162:165], v[210:213], v[98:101]
	s_setprio 0
	s_setprio 1
	v_mfma_f32_16x16x32_bf16 v[70:73], v[166:169], v[182:185], v[70:73]
	v_mfma_f32_16x16x32_bf16 v[66:69], v[174:177], v[182:185], v[66:69]
	v_mfma_f32_16x16x32_bf16 v[54:57], v[166:169], v[190:193], v[54:57]
	v_mfma_f32_16x16x32_bf16 v[50:53], v[174:177], v[190:193], v[50:53]
	v_mfma_f32_16x16x32_bf16 v[46:49], v[166:169], v[198:201], v[46:49]
	v_mfma_f32_16x16x32_bf16 v[42:45], v[174:177], v[198:201], v[42:45]
	v_mfma_f32_16x16x32_bf16 v[38:41], v[166:169], v[206:209], v[38:41]
	v_mfma_f32_16x16x32_bf16 v[34:37], v[174:177], v[206:209], v[34:37]
	v_mfma_f32_16x16x32_bf16 v[70:73], v[170:173], v[186:189], v[70:73]
	v_mfma_f32_16x16x32_bf16 v[66:69], v[178:181], v[186:189], v[66:69]
	v_mfma_f32_16x16x32_bf16 v[54:57], v[170:173], v[194:197], v[54:57]
	v_mfma_f32_16x16x32_bf16 v[50:53], v[178:181], v[194:197], v[50:53]
	v_mfma_f32_16x16x32_bf16 v[46:49], v[170:173], v[202:205], v[46:49]
	v_mfma_f32_16x16x32_bf16 v[42:45], v[178:181], v[202:205], v[42:45]
	v_mfma_f32_16x16x32_bf16 v[38:41], v[170:173], v[210:213], v[38:41]
	v_mfma_f32_16x16x32_bf16 v[34:37], v[178:181], v[210:213], v[34:37]
	s_setprio 0
	s_barrier
	s_add_i32 s24, s49, s29
	v_lshl_add_u64 v[152:153], v[152:153], 0, s[90:91]
	s_mov_b32 m0, s24
	ds_read_b128 v[182:185], v156 offset:49152
	ds_read_b128 v[186:189], v156 offset:50176
	ds_read_b128 v[190:193], v156 offset:51200
	ds_read_b128 v[194:197], v156 offset:52224
	ds_read_b128 v[198:201], v156 offset:53248
	ds_read_b128 v[202:205], v156 offset:54272
	ds_read_b128 v[206:209], v156 offset:55296
	ds_read_b128 v[210:213], v156 offset:56320
	global_load_lds_dwordx4 v[152:153], off
	s_add_i32 m0, s24, 0x2000
	s_add_u32 s22, s22, 0x40080
	v_lshl_add_u64 v[152:153], v[214:215], 0, s[90:91]
	s_addc_u32 s23, s23, 0
	s_add_i32 s24, s50, s29
	global_load_lds_dwordx4 v[152:153], off
	v_lshl_add_u64 v[152:153], s[22:23], 0, v[140:141]
	s_mov_b32 m0, s24
	s_nop 0
	global_load_lds_dwordx4 v[152:153], off
	v_lshl_add_u64 v[152:153], s[22:23], 0, v[144:145]
	s_add_i32 m0, s24, 0x2000
	s_nop 0
	global_load_lds_dwordx4 v[152:153], off
	v_lshl_add_u64 v[152:153], v[216:217], 0, s[90:91]
	s_mov_b32 m0, s35
	s_nop 0
	global_load_lds_dwordx4 v[152:153], off
	v_lshl_add_u64 v[152:153], v[218:219], 0, s[90:91]
	s_mov_b32 m0, s36
	s_nop 0
	global_load_lds_dwordx4 v[152:153], off
	s_waitcnt vmcnt(8)
	s_waitcnt lgkmcnt(0)
	s_barrier
	s_setprio 1
	s_waitcnt lgkmcnt(0)
	v_mfma_f32_16x16x32_bf16 v[94:97], v[134:137], v[182:185], v[94:97]
	v_mfma_f32_16x16x32_bf16 v[90:93], v[158:161], v[182:185], v[90:93]
	v_mfma_f32_16x16x32_bf16 v[86:89], v[134:137], v[190:193], v[86:89]
	v_mfma_f32_16x16x32_bf16 v[82:85], v[158:161], v[190:193], v[82:85]
	v_mfma_f32_16x16x32_bf16 v[78:81], v[134:137], v[198:201], v[78:81]
	v_mfma_f32_16x16x32_bf16 v[74:77], v[158:161], v[198:201], v[74:77]
	v_mfma_f32_16x16x32_bf16 v[62:65], v[134:137], v[206:209], v[62:65]
	v_mfma_f32_16x16x32_bf16 v[58:61], v[158:161], v[206:209], v[58:61]
	v_mfma_f32_16x16x32_bf16 v[94:97], v[148:151], v[186:189], v[94:97]
	v_mfma_f32_16x16x32_bf16 v[90:93], v[162:165], v[186:189], v[90:93]
	v_mfma_f32_16x16x32_bf16 v[86:89], v[148:151], v[194:197], v[86:89]
	v_mfma_f32_16x16x32_bf16 v[82:85], v[162:165], v[194:197], v[82:85]
	v_mfma_f32_16x16x32_bf16 v[78:81], v[148:151], v[202:205], v[78:81]
	v_mfma_f32_16x16x32_bf16 v[74:77], v[162:165], v[202:205], v[74:77]
	v_mfma_f32_16x16x32_bf16 v[62:65], v[148:151], v[210:213], v[62:65]
	v_mfma_f32_16x16x32_bf16 v[58:61], v[162:165], v[210:213], v[58:61]
	s_setprio 0
	s_setprio 1
	v_mfma_f32_16x16x32_bf16 v[30:33], v[166:169], v[182:185], v[30:33]
	v_mfma_f32_16x16x32_bf16 v[26:29], v[174:177], v[182:185], v[26:29]
	v_mfma_f32_16x16x32_bf16 v[22:25], v[166:169], v[190:193], v[22:25]
	v_mfma_f32_16x16x32_bf16 v[18:21], v[174:177], v[190:193], v[18:21]
	v_mfma_f32_16x16x32_bf16 v[14:17], v[166:169], v[198:201], v[14:17]
	v_mfma_f32_16x16x32_bf16 v[10:13], v[174:177], v[198:201], v[10:13]
	v_mfma_f32_16x16x32_bf16 v[6:9], v[166:169], v[206:209], v[6:9]
	v_mfma_f32_16x16x32_bf16 v[2:5], v[174:177], v[206:209], v[2:5]
	v_mfma_f32_16x16x32_bf16 v[30:33], v[170:173], v[186:189], v[30:33]
	v_mfma_f32_16x16x32_bf16 v[26:29], v[178:181], v[186:189], v[26:29]
	v_mfma_f32_16x16x32_bf16 v[22:25], v[170:173], v[194:197], v[22:25]
	v_mfma_f32_16x16x32_bf16 v[18:21], v[178:181], v[194:197], v[18:21]
	v_mfma_f32_16x16x32_bf16 v[14:17], v[170:173], v[202:205], v[14:17]
	v_mfma_f32_16x16x32_bf16 v[10:13], v[178:181], v[202:205], v[10:13]
	v_mfma_f32_16x16x32_bf16 v[6:9], v[170:173], v[210:213], v[6:9]
	v_mfma_f32_16x16x32_bf16 v[2:5], v[178:181], v[210:213], v[2:5]
	s_setprio 0
	s_barrier
	s_add_i32 s48, s48, 2
	s_add_u32 s46, s46, 0x100
	s_addc_u32 s47, s47, 0
	s_add_u32 s16, s16, 0x100
	s_addc_u32 s17, s17, 0

.LBB0_323:
	s_add_u32 s49, s26, 0x100
	s_addc_u32 s50, s27, 0
	s_mov_b32 s51, -2
	s_waitcnt vmcnt(0)
	s_add_u32 s26, s24, 0x100
	s_addc_u32 s27, s25, 0
	s_add_i32 s52, 0, 0x10000
	s_cmp_eq_u32 s51, 40
	s_cselect_b32 s31, s7, s27
	s_cselect_b32 s30, s6, s26
	s_cselect_b32 s29, s17, s50
	s_cselect_b32 s28, s16, s49
	s_add_i32 s53, 0, 0x14000
	v_add_u32_e32 v142, s52, v184
	v_add_u32_e32 v170, s53, v184
	ds_read_b128 v[130:133], v142
	ds_read_b128 v[134:137], v142 offset:1024
	ds_read_b128 v[138:141], v142 offset:2048
	ds_read_b128 v[142:145], v142 offset:3072
	ds_read_b128 v[146:149], v170
	ds_read_b128 v[150:153], v170 offset:1024
	ds_read_b128 v[166:169], v170 offset:2048
	ds_read_b128 v[170:173], v170 offset:3072
	v_lshl_add_u64 v[182:183], s[24:25], 0, v[164:165]
	s_add_i32 m0, s36, 0xc000
	ds_read_b128 v[174:177], v186
	ds_read_b128 v[178:181], v186 offset:1024
	ds_read_b128 v[188:191], v186 offset:2048
	ds_read_b128 v[192:195], v186 offset:3072
	ds_read_b128 v[196:199], v186 offset:4096
	ds_read_b128 v[200:203], v186 offset:5120
	ds_read_b128 v[204:207], v186 offset:6144
	ds_read_b128 v[208:211], v186 offset:7168
	global_load_lds_dwordx4 v[182:183], off
	v_lshl_add_u64 v[182:183], s[24:25], 0, v[162:163]
	s_add_i32 m0, s36, 0xe000
	s_nop 0
	global_load_lds_dwordx4 v[182:183], off
	s_waitcnt vmcnt(8)
	s_waitcnt lgkmcnt(0)
	s_barrier
	s_setprio 1
	s_waitcnt lgkmcnt(0)
	v_mfma_f32_16x16x32_bf16 v[126:129], v[130:133], v[174:177], 0
	v_mfma_f32_16x16x32_bf16 v[122:125], v[138:141], v[174:177], 0
	v_mfma_f32_16x16x32_bf16 v[110:113], v[130:133], v[188:191], 0
	v_mfma_f32_16x16x32_bf16 v[106:109], v[138:141], v[188:191], 0
	v_mfma_f32_16x16x32_bf16 v[94:97], v[130:133], v[196:199], 0
	v_mfma_f32_16x16x32_bf16 v[90:93], v[138:141], v[196:199], 0
	v_mfma_f32_16x16x32_bf16 v[78:81], v[130:133], v[204:207], 0
	v_mfma_f32_16x16x32_bf16 v[74:77], v[138:141], v[204:207], 0
	v_mfma_f32_16x16x32_bf16 v[126:129], v[134:137], v[178:181], v[126:129]
	v_mfma_f32_16x16x32_bf16 v[122:125], v[142:145], v[178:181], v[122:125]
	v_mfma_f32_16x16x32_bf16 v[110:113], v[134:137], v[192:195], v[110:113]
	v_mfma_f32_16x16x32_bf16 v[106:109], v[142:145], v[192:195], v[106:109]
	v_mfma_f32_16x16x32_bf16 v[94:97], v[134:137], v[200:203], v[94:97]
	v_mfma_f32_16x16x32_bf16 v[90:93], v[142:145], v[200:203], v[90:93]
	v_mfma_f32_16x16x32_bf16 v[78:81], v[134:137], v[208:211], v[78:81]
	v_mfma_f32_16x16x32_bf16 v[74:77], v[142:145], v[208:211], v[74:77]
	s_setprio 0
	s_setprio 1
	v_mfma_f32_16x16x32_bf16 v[118:121], v[146:149], v[174:177], 0
	v_mfma_f32_16x16x32_bf16 v[114:117], v[166:169], v[174:177], 0
	v_mfma_f32_16x16x32_bf16 v[102:105], v[146:149], v[188:191], 0
	v_mfma_f32_16x16x32_bf16 v[98:101], v[166:169], v[188:191], 0
	v_mfma_f32_16x16x32_bf16 v[86:89], v[146:149], v[196:199], 0
	v_mfma_f32_16x16x32_bf16 v[82:85], v[166:169], v[196:199], 0
	v_mfma_f32_16x16x32_bf16 v[70:73], v[146:149], v[204:207], 0
	v_mfma_f32_16x16x32_bf16 v[66:69], v[166:169], v[204:207], 0
	v_mfma_f32_16x16x32_bf16 v[118:121], v[150:153], v[178:181], v[118:121]
	v_mfma_f32_16x16x32_bf16 v[114:117], v[170:173], v[178:181], v[114:117]
	v_mfma_f32_16x16x32_bf16 v[102:105], v[150:153], v[192:195], v[102:105]
	v_mfma_f32_16x16x32_bf16 v[98:101], v[170:173], v[192:195], v[98:101]
	v_mfma_f32_16x16x32_bf16 v[86:89], v[150:153], v[200:203], v[86:89]
	v_mfma_f32_16x16x32_bf16 v[82:85], v[170:173], v[200:203], v[82:85]
	v_mfma_f32_16x16x32_bf16 v[70:73], v[150:153], v[208:211], v[70:73]
	v_mfma_f32_16x16x32_bf16 v[66:69], v[170:173], v[208:211], v[66:69]
	s_setprio 0
	s_barrier
	s_add_i32 s24, s52, s35
	v_lshl_add_u64 v[182:183], s[28:29], 0, v[156:157]
	s_mov_b32 m0, s24
	ds_read_b128 v[174:177], v186 offset:16384
	ds_read_b128 v[178:181], v186 offset:17408
	ds_read_b128 v[188:191], v186 offset:18432
	ds_read_b128 v[192:195], v186 offset:19456
	ds_read_b128 v[196:199], v186 offset:20480
	ds_read_b128 v[200:203], v186 offset:21504
	ds_read_b128 v[204:207], v186 offset:22528
	ds_read_b128 v[208:211], v186 offset:23552
	global_load_lds_dwordx4 v[182:183], off
	s_add_i32 m0, s24, 0x2000
	s_add_u32 s24, s28, 0xb0000
	v_lshl_add_u64 v[212:213], s[28:29], 0, v[160:161]
	s_addc_u32 s25, s29, 0
	s_add_i32 s52, s53, s35
	global_load_lds_dwordx4 v[212:213], off
	v_lshl_add_u64 v[214:215], s[24:25], 0, v[156:157]
	s_mov_b32 m0, s52
	v_lshl_add_u64 v[216:217], s[30:31], 0, v[158:159]
	global_load_lds_dwordx4 v[214:215], off
	v_lshl_add_u64 v[214:215], s[24:25], 0, v[160:161]
	s_add_i32 m0, s52, 0x2000
	s_nop 0
	global_load_lds_dwordx4 v[214:215], off
	v_lshl_add_u64 v[214:215], s[30:31], 0, v[154:155]
	s_mov_b32 m0, s36
	s_nop 0
	global_load_lds_dwordx4 v[214:215], off
	s_mov_b32 m0, s37
	s_nop 0
	global_load_lds_dwordx4 v[216:217], off
	s_waitcnt vmcnt(8)
	s_waitcnt lgkmcnt(0)
	s_barrier
	s_setprio 1
	s_waitcnt lgkmcnt(0)
	v_mfma_f32_16x16x32_bf16 v[62:65], v[130:133], v[174:177], 0
	v_mfma_f32_16x16x32_bf16 v[58:61], v[138:141], v[174:177], 0
	v_mfma_f32_16x16x32_bf16 v[46:49], v[130:133], v[188:191], 0
	v_mfma_f32_16x16x32_bf16 v[42:45], v[138:141], v[188:191], 0
	v_mfma_f32_16x16x32_bf16 v[30:33], v[130:133], v[196:199], 0
	v_mfma_f32_16x16x32_bf16 v[26:29], v[138:141], v[196:199], 0
	v_mfma_f32_16x16x32_bf16 v[14:17], v[130:133], v[204:207], 0
	v_mfma_f32_16x16x32_bf16 v[10:13], v[138:141], v[204:207], 0
	v_mfma_f32_16x16x32_bf16 v[62:65], v[134:137], v[178:181], v[62:65]
	v_mfma_f32_16x16x32_bf16 v[58:61], v[142:145], v[178:181], v[58:61]
	v_mfma_f32_16x16x32_bf16 v[46:49], v[134:137], v[192:195], v[46:49]
	v_mfma_f32_16x16x32_bf16 v[42:45], v[142:145], v[192:195], v[42:45]
	v_mfma_f32_16x16x32_bf16 v[30:33], v[134:137], v[200:203], v[30:33]
	v_mfma_f32_16x16x32_bf16 v[26:29], v[142:145], v[200:203], v[26:29]
	v_mfma_f32_16x16x32_bf16 v[14:17], v[134:137], v[208:211], v[14:17]
	v_mfma_f32_16x16x32_bf16 v[10:13], v[142:145], v[208:211], v[10:13]
	s_setprio 0
	s_setprio 1
	v_mfma_f32_16x16x32_bf16 v[54:57], v[146:149], v[174:177], 0
	v_mfma_f32_16x16x32_bf16 v[50:53], v[166:169], v[174:177], 0
	v_mfma_f32_16x16x32_bf16 v[38:41], v[146:149], v[188:191], 0
	v_mfma_f32_16x16x32_bf16 v[34:37], v[166:169], v[188:191], 0
	v_mfma_f32_16x16x32_bf16 v[22:25], v[146:149], v[196:199], 0
	v_mfma_f32_16x16x32_bf16 v[18:21], v[166:169], v[196:199], 0
	v_mfma_f32_16x16x32_bf16 v[6:9], v[146:149], v[204:207], 0
	v_mfma_f32_16x16x32_bf16 v[2:5], v[166:169], v[204:207], 0
	v_mfma_f32_16x16x32_bf16 v[54:57], v[150:153], v[178:181], v[54:57]
	v_mfma_f32_16x16x32_bf16 v[50:53], v[170:173], v[178:181], v[50:53]
	v_mfma_f32_16x16x32_bf16 v[38:41], v[150:153], v[192:195], v[38:41]
	v_mfma_f32_16x16x32_bf16 v[34:37], v[170:173], v[192:195], v[34:37]
	v_mfma_f32_16x16x32_bf16 v[22:25], v[150:153], v[200:203], v[22:25]
	v_mfma_f32_16x16x32_bf16 v[18:21], v[170:173], v[200:203], v[18:21]
	v_mfma_f32_16x16x32_bf16 v[6:9], v[150:153], v[208:211], v[6:9]
	v_mfma_f32_16x16x32_bf16 v[2:5], v[170:173], v[208:211], v[2:5]
	s_setprio 0
	s_barrier
	s_add_i32 s52, 0, 0x18000
	s_add_i32 s53, 0, 0x1c000
	v_add_u32_e32 v142, s52, v184
	v_add_u32_e32 v170, s53, v184
	ds_read_b128 v[130:133], v142
	ds_read_b128 v[134:137], v142 offset:1024
	ds_read_b128 v[138:141], v142 offset:2048
	ds_read_b128 v[142:145], v142 offset:3072
	ds_read_b128 v[146:149], v170
	ds_read_b128 v[150:153], v170 offset:1024
	ds_read_b128 v[166:169], v170 offset:2048
	ds_read_b128 v[170:173], v170 offset:3072
	s_add_u32 s24, s30, 0xb0000
	s_addc_u32 s25, s31, 0
	s_mov_b32 m0, s38
	v_lshl_add_u64 v[218:219], s[24:25], 0, v[154:155]
	ds_read_b128 v[174:177], v186 offset:32768
	ds_read_b128 v[178:181], v186 offset:33792
	ds_read_b128 v[188:191], v186 offset:34816
	ds_read_b128 v[192:195], v186 offset:35840
	ds_read_b128 v[196:199], v186 offset:36864
	ds_read_b128 v[200:203], v186 offset:37888
	ds_read_b128 v[204:207], v186 offset:38912
	ds_read_b128 v[208:211], v186 offset:39936
	global_load_lds_dwordx4 v[218:219], off
	v_lshl_add_u64 v[218:219], s[24:25], 0, v[158:159]
	s_mov_b32 m0, s39
	s_nop 0
	global_load_lds_dwordx4 v[218:219], off
	s_waitcnt vmcnt(8)
	s_waitcnt lgkmcnt(0)
	s_barrier
	s_setprio 1
	s_waitcnt lgkmcnt(0)
	v_mfma_f32_16x16x32_bf16 v[126:129], v[130:133], v[174:177], v[126:129]
	v_mfma_f32_16x16x32_bf16 v[122:125], v[138:141], v[174:177], v[122:125]
	v_mfma_f32_16x16x32_bf16 v[110:113], v[130:133], v[188:191], v[110:113]
	v_mfma_f32_16x16x32_bf16 v[106:109], v[138:141], v[188:191], v[106:109]
	v_mfma_f32_16x16x32_bf16 v[94:97], v[130:133], v[196:199], v[94:97]
	v_mfma_f32_16x16x32_bf16 v[90:93], v[138:141], v[196:199], v[90:93]
	v_mfma_f32_16x16x32_bf16 v[78:81], v[130:133], v[204:207], v[78:81]
	v_mfma_f32_16x16x32_bf16 v[74:77], v[138:141], v[204:207], v[74:77]
	v_mfma_f32_16x16x32_bf16 v[126:129], v[134:137], v[178:181], v[126:129]
	v_mfma_f32_16x16x32_bf16 v[122:125], v[142:145], v[178:181], v[122:125]
	v_mfma_f32_16x16x32_bf16 v[110:113], v[134:137], v[192:195], v[110:113]
	v_mfma_f32_16x16x32_bf16 v[106:109], v[142:145], v[192:195], v[106:109]
	v_mfma_f32_16x16x32_bf16 v[94:97], v[134:137], v[200:203], v[94:97]
	v_mfma_f32_16x16x32_bf16 v[90:93], v[142:145], v[200:203], v[90:93]
	v_mfma_f32_16x16x32_bf16 v[78:81], v[134:137], v[208:211], v[78:81]
	v_mfma_f32_16x16x32_bf16 v[74:77], v[142:145], v[208:211], v[74:77]
	s_setprio 0
	s_setprio 1
	v_mfma_f32_16x16x32_bf16 v[118:121], v[146:149], v[174:177], v[118:121]
	v_mfma_f32_16x16x32_bf16 v[114:117], v[166:169], v[174:177], v[114:117]
	v_mfma_f32_16x16x32_bf16 v[102:105], v[146:149], v[188:191], v[102:105]
	v_mfma_f32_16x16x32_bf16 v[98:101], v[166:169], v[188:191], v[98:101]
	v_mfma_f32_16x16x32_bf16 v[86:89], v[146:149], v[196:199], v[86:89]
	v_mfma_f32_16x16x32_bf16 v[82:85], v[166:169], v[196:199], v[82:85]
	v_mfma_f32_16x16x32_bf16 v[70:73], v[146:149], v[204:207], v[70:73]
	v_mfma_f32_16x16x32_bf16 v[66:69], v[166:169], v[204:207], v[66:69]
	v_mfma_f32_16x16x32_bf16 v[118:121], v[150:153], v[178:181], v[118:121]
	v_mfma_f32_16x16x32_bf16 v[114:117], v[170:173], v[178:181], v[114:117]
	v_mfma_f32_16x16x32_bf16 v[102:105], v[150:153], v[192:195], v[102:105]
	v_mfma_f32_16x16x32_bf16 v[98:101], v[170:173], v[192:195], v[98:101]
	v_mfma_f32_16x16x32_bf16 v[86:89], v[150:153], v[200:203], v[86:89]
	v_mfma_f32_16x16x32_bf16 v[82:85], v[170:173], v[200:203], v[82:85]
	v_mfma_f32_16x16x32_bf16 v[70:73], v[150:153], v[208:211], v[70:73]
	v_mfma_f32_16x16x32_bf16 v[66:69], v[170:173], v[208:211], v[66:69]
	s_setprio 0
	s_barrier
	s_add_i32 s24, s52, s35
	v_lshl_add_u64 v[182:183], v[182:183], 0, s[90:91]
	s_mov_b32 m0, s24
	ds_read_b128 v[174:177], v186 offset:49152
	ds_read_b128 v[178:181], v186 offset:50176
	ds_read_b128 v[188:191], v186 offset:51200
	ds_read_b128 v[192:195], v186 offset:52224
	ds_read_b128 v[196:199], v186 offset:53248
	ds_read_b128 v[200:203], v186 offset:54272
	ds_read_b128 v[204:207], v186 offset:55296
	ds_read_b128 v[208:211], v186 offset:56320
	global_load_lds_dwordx4 v[182:183], off
	s_add_i32 m0, s24, 0x2000
	s_add_u32 s24, s28, 0xb0080
	v_lshl_add_u64 v[182:183], v[212:213], 0, s[90:91]
	s_addc_u32 s25, s29, 0
	s_add_i32 s28, s53, s35
	global_load_lds_dwordx4 v[182:183], off
	v_lshl_add_u64 v[182:183], s[24:25], 0, v[156:157]
	s_mov_b32 m0, s28
	s_nop 0
	global_load_lds_dwordx4 v[182:183], off
	v_lshl_add_u64 v[182:183], s[24:25], 0, v[160:161]
	s_add_i32 m0, s28, 0x2000
	s_nop 0
	global_load_lds_dwordx4 v[182:183], off
	v_lshl_add_u64 v[182:183], v[214:215], 0, s[90:91]
	s_mov_b32 m0, s42
	s_nop 0
	global_load_lds_dwordx4 v[182:183], off
	v_lshl_add_u64 v[182:183], v[216:217], 0, s[90:91]
	s_mov_b32 m0, s43
	s_nop 0
	global_load_lds_dwordx4 v[182:183], off
	s_waitcnt vmcnt(8)
	s_waitcnt lgkmcnt(0)
	s_barrier
	s_setprio 1
	s_waitcnt lgkmcnt(0)
	v_mfma_f32_16x16x32_bf16 v[62:65], v[130:133], v[174:177], v[62:65]
	v_mfma_f32_16x16x32_bf16 v[58:61], v[138:141], v[174:177], v[58:61]
	v_mfma_f32_16x16x32_bf16 v[46:49], v[130:133], v[188:191], v[46:49]
	v_mfma_f32_16x16x32_bf16 v[42:45], v[138:141], v[188:191], v[42:45]
	v_mfma_f32_16x16x32_bf16 v[30:33], v[130:133], v[196:199], v[30:33]
	v_mfma_f32_16x16x32_bf16 v[26:29], v[138:141], v[196:199], v[26:29]
	v_mfma_f32_16x16x32_bf16 v[14:17], v[130:133], v[204:207], v[14:17]
	v_mfma_f32_16x16x32_bf16 v[10:13], v[138:141], v[204:207], v[10:13]
	v_mfma_f32_16x16x32_bf16 v[62:65], v[134:137], v[178:181], v[62:65]
	v_mfma_f32_16x16x32_bf16 v[58:61], v[142:145], v[178:181], v[58:61]
	v_mfma_f32_16x16x32_bf16 v[46:49], v[134:137], v[192:195], v[46:49]
	v_mfma_f32_16x16x32_bf16 v[42:45], v[142:145], v[192:195], v[42:45]
	v_mfma_f32_16x16x32_bf16 v[30:33], v[134:137], v[200:203], v[30:33]
	v_mfma_f32_16x16x32_bf16 v[26:29], v[142:145], v[200:203], v[26:29]
	v_mfma_f32_16x16x32_bf16 v[14:17], v[134:137], v[208:211], v[14:17]
	v_mfma_f32_16x16x32_bf16 v[10:13], v[142:145], v[208:211], v[10:13]
	s_setprio 0
	s_setprio 1
	v_mfma_f32_16x16x32_bf16 v[54:57], v[146:149], v[174:177], v[54:57]
	v_mfma_f32_16x16x32_bf16 v[50:53], v[166:169], v[174:177], v[50:53]
	v_mfma_f32_16x16x32_bf16 v[38:41], v[146:149], v[188:191], v[38:41]
	v_mfma_f32_16x16x32_bf16 v[34:37], v[166:169], v[188:191], v[34:37]
	v_mfma_f32_16x16x32_bf16 v[22:25], v[146:149], v[196:199], v[22:25]
	v_mfma_f32_16x16x32_bf16 v[18:21], v[166:169], v[196:199], v[18:21]
	v_mfma_f32_16x16x32_bf16 v[6:9], v[146:149], v[204:207], v[6:9]
	v_mfma_f32_16x16x32_bf16 v[2:5], v[166:169], v[204:207], v[2:5]
	v_mfma_f32_16x16x32_bf16 v[54:57], v[150:153], v[178:181], v[54:57]
	v_mfma_f32_16x16x32_bf16 v[50:53], v[170:173], v[178:181], v[50:53]
	v_mfma_f32_16x16x32_bf16 v[38:41], v[150:153], v[192:195], v[38:41]
	v_mfma_f32_16x16x32_bf16 v[34:37], v[170:173], v[192:195], v[34:37]
	v_mfma_f32_16x16x32_bf16 v[22:25], v[150:153], v[200:203], v[22:25]
	v_mfma_f32_16x16x32_bf16 v[18:21], v[170:173], v[200:203], v[18:21]
	v_mfma_f32_16x16x32_bf16 v[6:9], v[150:153], v[208:211], v[6:9]
	v_mfma_f32_16x16x32_bf16 v[2:5], v[170:173], v[208:211], v[2:5]
	s_setprio 0
	s_barrier
	s_add_i32 s51, s51, 2
	s_add_u32 s49, s49, 0x100
	s_addc_u32 s50, s50, 0
	s_mov_b64 s[24:25], s[26:27]

.LBB0_360:
	s_lshl_b32 s10, s35, 8
	s_ashr_i32 s11, s10, 31
	s_lshl_b64 s[10:11], s[10:11], 11
	s_add_u32 s10, s80, s10
	s_addc_u32 s11, s81, s11
	s_and_b64 s[12:13], s[2:3], exec
	s_cselect_b32 s38, s11, s17
	s_cselect_b32 s39, s10, s16
	s_lshl_b32 s12, s34, 8
	s_ashr_i32 s13, s12, 31
	s_lshl_b64 s[12:13], s[12:13], 11
	s_add_u32 s12, s22, s12
	s_addc_u32 s13, s23, s13
	s_and_b64 s[20:21], s[2:3], exec
	s_cselect_b32 s40, s13, s15
	s_cselect_b32 s41, s12, s14
	s_add_u32 s42, s14, 0x100
	s_addc_u32 s43, s15, 0
	s_add_u32 s14, s16, 0x40080
	s_addc_u32 s15, s17, 0
	s_mov_b32 s44, -2
	s_waitcnt vmcnt(0)
	s_add_u32 s16, s14, 0xfffc0080
	s_addc_u32 s17, s15, -1
	s_add_i32 s45, 0, 0x10000
	s_cmp_eq_u32 s44, 12
	s_cselect_b32 s21, s38, s17
	s_cselect_b32 s20, s39, s16
	v_add_u32_e32 v148, s45, v151
	s_cselect_b32 s17, s40, s43
	s_cselect_b32 s16, s41, s42
	s_add_i32 s48, 0, 0x14000
	ds_read_b128 v[144:147], v148
	ds_read_b128 v[160:163], v148 offset:1024
	ds_read_b128 v[164:167], v148 offset:2048
	ds_read_b128 v[168:171], v148 offset:3072
	v_add_u32_e32 v148, s48, v151
	ds_read_b128 v[172:175], v148
	ds_read_b128 v[176:179], v148 offset:1024
	ds_read_b128 v[180:183], v148 offset:2048
	ds_read_b128 v[184:187], v148 offset:3072
	v_lshl_add_u64 v[148:149], s[14:15], 0, v[142:143]
	s_add_i32 m0, s26, 0xc000
	ds_read_b128 v[188:191], v159
	ds_read_b128 v[192:195], v159 offset:1024
	ds_read_b128 v[196:199], v159 offset:2048
	ds_read_b128 v[200:203], v159 offset:3072
	ds_read_b128 v[204:207], v159 offset:4096
	ds_read_b128 v[208:211], v159 offset:5120
	ds_read_b128 v[212:215], v159 offset:6144
	ds_read_b128 v[216:219], v159 offset:7168
	global_load_lds_dwordx4 v[148:149], off
	v_lshl_add_u64 v[148:149], s[14:15], 0, v[140:141]
	s_add_i32 m0, s26, 0xe000
	s_nop 0
	global_load_lds_dwordx4 v[148:149], off
	s_waitcnt vmcnt(8)
	s_waitcnt lgkmcnt(0)
	s_barrier
	s_setprio 1
	s_waitcnt lgkmcnt(0)
	v_mfma_f32_16x16x32_bf16 v[126:129], v[144:147], v[188:191], 0
	v_mfma_f32_16x16x32_bf16 v[122:125], v[164:167], v[188:191], 0
	v_mfma_f32_16x16x32_bf16 v[110:113], v[144:147], v[196:199], 0
	v_mfma_f32_16x16x32_bf16 v[106:109], v[164:167], v[196:199], 0
	v_mfma_f32_16x16x32_bf16 v[94:97], v[144:147], v[204:207], 0
	v_mfma_f32_16x16x32_bf16 v[90:93], v[164:167], v[204:207], 0
	v_mfma_f32_16x16x32_bf16 v[78:81], v[144:147], v[212:215], 0
	v_mfma_f32_16x16x32_bf16 v[74:77], v[164:167], v[212:215], 0
	v_mfma_f32_16x16x32_bf16 v[126:129], v[160:163], v[192:195], v[126:129]
	v_mfma_f32_16x16x32_bf16 v[122:125], v[168:171], v[192:195], v[122:125]
	v_mfma_f32_16x16x32_bf16 v[110:113], v[160:163], v[200:203], v[110:113]
	v_mfma_f32_16x16x32_bf16 v[106:109], v[168:171], v[200:203], v[106:109]
	v_mfma_f32_16x16x32_bf16 v[94:97], v[160:163], v[208:211], v[94:97]
	v_mfma_f32_16x16x32_bf16 v[90:93], v[168:171], v[208:211], v[90:93]
	v_mfma_f32_16x16x32_bf16 v[78:81], v[160:163], v[216:219], v[78:81]
	v_mfma_f32_16x16x32_bf16 v[74:77], v[168:171], v[216:219], v[74:77]
	s_setprio 0
	s_setprio 1
	v_mfma_f32_16x16x32_bf16 v[118:121], v[172:175], v[188:191], 0
	v_mfma_f32_16x16x32_bf16 v[114:117], v[180:183], v[188:191], 0
	v_mfma_f32_16x16x32_bf16 v[102:105], v[172:175], v[196:199], 0
	v_mfma_f32_16x16x32_bf16 v[98:101], v[180:183], v[196:199], 0
	v_mfma_f32_16x16x32_bf16 v[86:89], v[172:175], v[204:207], 0
	v_mfma_f32_16x16x32_bf16 v[82:85], v[180:183], v[204:207], 0
	v_mfma_f32_16x16x32_bf16 v[70:73], v[172:175], v[212:215], 0
	v_mfma_f32_16x16x32_bf16 v[66:69], v[180:183], v[212:215], 0
	v_mfma_f32_16x16x32_bf16 v[118:121], v[176:179], v[192:195], v[118:121]
	v_mfma_f32_16x16x32_bf16 v[114:117], v[184:187], v[192:195], v[114:117]
	v_mfma_f32_16x16x32_bf16 v[102:105], v[176:179], v[200:203], v[102:105]
	v_mfma_f32_16x16x32_bf16 v[98:101], v[184:187], v[200:203], v[98:101]
	v_mfma_f32_16x16x32_bf16 v[86:89], v[176:179], v[208:211], v[86:89]
	v_mfma_f32_16x16x32_bf16 v[82:85], v[184:187], v[208:211], v[82:85]
	v_mfma_f32_16x16x32_bf16 v[70:73], v[176:179], v[216:219], v[70:73]
	v_mfma_f32_16x16x32_bf16 v[66:69], v[184:187], v[216:219], v[66:69]
	s_setprio 0
	s_barrier
	s_add_i32 s45, s45, s24
	v_lshl_add_u64 v[148:149], s[16:17], 0, v[134:135]
	s_mov_b32 m0, s45
	ds_read_b128 v[188:191], v159 offset:16384
	ds_read_b128 v[192:195], v159 offset:17408
	ds_read_b128 v[196:199], v159 offset:18432
	ds_read_b128 v[200:203], v159 offset:19456
	ds_read_b128 v[204:207], v159 offset:20480
	ds_read_b128 v[208:211], v159 offset:21504
	ds_read_b128 v[212:215], v159 offset:22528
	ds_read_b128 v[216:219], v159 offset:23552
	global_load_lds_dwordx4 v[148:149], off
	s_add_i32 m0, s45, 0x2000
	s_add_u32 s46, s16, 0x40000
	v_lshl_add_u64 v[152:153], s[16:17], 0, v[130:131]
	s_addc_u32 s47, s17, 0
	s_add_i32 s45, s48, s24
	global_load_lds_dwordx4 v[152:153], off
	v_lshl_add_u64 v[156:157], s[46:47], 0, v[134:135]
	s_mov_b32 m0, s45
	v_lshl_add_u64 v[220:221], s[20:21], 0, v[132:133]
	global_load_lds_dwordx4 v[156:157], off
	v_lshl_add_u64 v[156:157], s[46:47], 0, v[130:131]
	s_add_i32 m0, s45, 0x2000
	s_nop 0
	global_load_lds_dwordx4 v[156:157], off
	v_lshl_add_u64 v[156:157], s[20:21], 0, v[136:137]
	s_mov_b32 m0, s26
	s_nop 0
	global_load_lds_dwordx4 v[156:157], off
	s_mov_b32 m0, s27
	s_nop 0
	global_load_lds_dwordx4 v[220:221], off
	s_waitcnt vmcnt(8)
	s_waitcnt lgkmcnt(0)
	s_barrier
	s_setprio 1
	s_waitcnt lgkmcnt(0)
	v_mfma_f32_16x16x32_bf16 v[62:65], v[144:147], v[188:191], 0
	v_mfma_f32_16x16x32_bf16 v[58:61], v[164:167], v[188:191], 0
	v_mfma_f32_16x16x32_bf16 v[46:49], v[144:147], v[196:199], 0
	v_mfma_f32_16x16x32_bf16 v[42:45], v[164:167], v[196:199], 0
	v_mfma_f32_16x16x32_bf16 v[30:33], v[144:147], v[204:207], 0
	v_mfma_f32_16x16x32_bf16 v[26:29], v[164:167], v[204:207], 0
	v_mfma_f32_16x16x32_bf16 v[14:17], v[144:147], v[212:215], 0
	v_mfma_f32_16x16x32_bf16 v[10:13], v[164:167], v[212:215], 0
	v_mfma_f32_16x16x32_bf16 v[62:65], v[160:163], v[192:195], v[62:65]
	v_mfma_f32_16x16x32_bf16 v[58:61], v[168:171], v[192:195], v[58:61]
	v_mfma_f32_16x16x32_bf16 v[46:49], v[160:163], v[200:203], v[46:49]
	v_mfma_f32_16x16x32_bf16 v[42:45], v[168:171], v[200:203], v[42:45]
	v_mfma_f32_16x16x32_bf16 v[30:33], v[160:163], v[208:211], v[30:33]
	v_mfma_f32_16x16x32_bf16 v[26:29], v[168:171], v[208:211], v[26:29]
	v_mfma_f32_16x16x32_bf16 v[14:17], v[160:163], v[216:219], v[14:17]
	v_mfma_f32_16x16x32_bf16 v[10:13], v[168:171], v[216:219], v[10:13]
	s_setprio 0
	s_setprio 1
	v_mfma_f32_16x16x32_bf16 v[54:57], v[172:175], v[188:191], 0
	v_mfma_f32_16x16x32_bf16 v[50:53], v[180:183], v[188:191], 0
	v_mfma_f32_16x16x32_bf16 v[38:41], v[172:175], v[196:199], 0
	v_mfma_f32_16x16x32_bf16 v[34:37], v[180:183], v[196:199], 0
	v_mfma_f32_16x16x32_bf16 v[22:25], v[172:175], v[204:207], 0
	v_mfma_f32_16x16x32_bf16 v[18:21], v[180:183], v[204:207], 0
	v_mfma_f32_16x16x32_bf16 v[6:9], v[172:175], v[212:215], 0
	v_mfma_f32_16x16x32_bf16 v[2:5], v[180:183], v[212:215], 0
	v_mfma_f32_16x16x32_bf16 v[54:57], v[176:179], v[192:195], v[54:57]
	v_mfma_f32_16x16x32_bf16 v[50:53], v[184:187], v[192:195], v[50:53]
	v_mfma_f32_16x16x32_bf16 v[38:41], v[176:179], v[200:203], v[38:41]
	v_mfma_f32_16x16x32_bf16 v[34:37], v[184:187], v[200:203], v[34:37]
	v_mfma_f32_16x16x32_bf16 v[22:25], v[176:179], v[208:211], v[22:25]
	v_mfma_f32_16x16x32_bf16 v[18:21], v[184:187], v[208:211], v[18:21]
	v_mfma_f32_16x16x32_bf16 v[6:9], v[176:179], v[216:219], v[6:9]
	v_mfma_f32_16x16x32_bf16 v[2:5], v[184:187], v[216:219], v[2:5]
	s_setprio 0
	s_barrier
	s_add_i32 s45, 0, 0x18000
	v_add_u32_e32 v150, s45, v151
	s_add_i32 s46, 0, 0x1c000
	ds_read_b128 v[144:147], v150
	ds_read_b128 v[160:163], v150 offset:1024
	ds_read_b128 v[164:167], v150 offset:2048
	ds_read_b128 v[168:171], v150 offset:3072
	v_add_u32_e32 v150, s46, v151
	ds_read_b128 v[172:175], v150
	ds_read_b128 v[176:179], v150 offset:1024
	ds_read_b128 v[180:183], v150 offset:2048
	ds_read_b128 v[184:187], v150 offset:3072
	s_add_u32 s20, s20, 0x40000
	s_addc_u32 s21, s21, 0
	s_mov_b32 m0, s28
	v_lshl_add_u64 v[222:223], s[20:21], 0, v[136:137]
	ds_read_b128 v[188:191], v159 offset:32768
	ds_read_b128 v[192:195], v159 offset:33792
	ds_read_b128 v[196:199], v159 offset:34816
	ds_read_b128 v[200:203], v159 offset:35840
	ds_read_b128 v[204:207], v159 offset:36864
	ds_read_b128 v[208:211], v159 offset:37888
	ds_read_b128 v[212:215], v159 offset:38912
	ds_read_b128 v[216:219], v159 offset:39936
	global_load_lds_dwordx4 v[222:223], off
	v_lshl_add_u64 v[222:223], s[20:21], 0, v[132:133]
	s_mov_b32 m0, s29
	s_nop 0
	global_load_lds_dwordx4 v[222:223], off
	s_waitcnt vmcnt(8)
	s_waitcnt lgkmcnt(0)
	s_barrier
	s_setprio 1
	s_waitcnt lgkmcnt(0)
	v_mfma_f32_16x16x32_bf16 v[126:129], v[144:147], v[188:191], v[126:129]
	v_mfma_f32_16x16x32_bf16 v[122:125], v[164:167], v[188:191], v[122:125]
	v_mfma_f32_16x16x32_bf16 v[110:113], v[144:147], v[196:199], v[110:113]
	v_mfma_f32_16x16x32_bf16 v[106:109], v[164:167], v[196:199], v[106:109]
	v_mfma_f32_16x16x32_bf16 v[94:97], v[144:147], v[204:207], v[94:97]
	v_mfma_f32_16x16x32_bf16 v[90:93], v[164:167], v[204:207], v[90:93]
	v_mfma_f32_16x16x32_bf16 v[78:81], v[144:147], v[212:215], v[78:81]
	v_mfma_f32_16x16x32_bf16 v[74:77], v[164:167], v[212:215], v[74:77]
	v_mfma_f32_16x16x32_bf16 v[126:129], v[160:163], v[192:195], v[126:129]
	v_mfma_f32_16x16x32_bf16 v[122:125], v[168:171], v[192:195], v[122:125]
	v_mfma_f32_16x16x32_bf16 v[110:113], v[160:163], v[200:203], v[110:113]
	v_mfma_f32_16x16x32_bf16 v[106:109], v[168:171], v[200:203], v[106:109]
	v_mfma_f32_16x16x32_bf16 v[94:97], v[160:163], v[208:211], v[94:97]
	v_mfma_f32_16x16x32_bf16 v[90:93], v[168:171], v[208:211], v[90:93]
	v_mfma_f32_16x16x32_bf16 v[78:81], v[160:163], v[216:219], v[78:81]
	v_mfma_f32_16x16x32_bf16 v[74:77], v[168:171], v[216:219], v[74:77]
	s_setprio 0
	s_setprio 1
	v_mfma_f32_16x16x32_bf16 v[118:121], v[172:175], v[188:191], v[118:121]
	v_mfma_f32_16x16x32_bf16 v[114:117], v[180:183], v[188:191], v[114:117]
	v_mfma_f32_16x16x32_bf16 v[102:105], v[172:175], v[196:199], v[102:105]
	v_mfma_f32_16x16x32_bf16 v[98:101], v[180:183], v[196:199], v[98:101]
	v_mfma_f32_16x16x32_bf16 v[86:89], v[172:175], v[204:207], v[86:89]
	v_mfma_f32_16x16x32_bf16 v[82:85], v[180:183], v[204:207], v[82:85]
	v_mfma_f32_16x16x32_bf16 v[70:73], v[172:175], v[212:215], v[70:73]
	v_mfma_f32_16x16x32_bf16 v[66:69], v[180:183], v[212:215], v[66:69]
	v_mfma_f32_16x16x32_bf16 v[118:121], v[176:179], v[192:195], v[118:121]
	v_mfma_f32_16x16x32_bf16 v[114:117], v[184:187], v[192:195], v[114:117]
	v_mfma_f32_16x16x32_bf16 v[102:105], v[176:179], v[200:203], v[102:105]
	v_mfma_f32_16x16x32_bf16 v[98:101], v[184:187], v[200:203], v[98:101]
	v_mfma_f32_16x16x32_bf16 v[86:89], v[176:179], v[208:211], v[86:89]
	v_mfma_f32_16x16x32_bf16 v[82:85], v[184:187], v[208:211], v[82:85]
	v_mfma_f32_16x16x32_bf16 v[70:73], v[176:179], v[216:219], v[70:73]
	v_mfma_f32_16x16x32_bf16 v[66:69], v[184:187], v[216:219], v[66:69]
	s_setprio 0
	s_barrier
	s_add_i32 s20, s45, s24
	v_lshl_add_u64 v[148:149], v[148:149], 0, s[90:91]
	s_mov_b32 m0, s20
	ds_read_b128 v[188:191], v159 offset:49152
	ds_read_b128 v[192:195], v159 offset:50176
	ds_read_b128 v[196:199], v159 offset:51200
	ds_read_b128 v[200:203], v159 offset:52224
	ds_read_b128 v[204:207], v159 offset:53248
	ds_read_b128 v[208:211], v159 offset:54272
	ds_read_b128 v[212:215], v159 offset:55296
	ds_read_b128 v[216:219], v159 offset:56320
	global_load_lds_dwordx4 v[148:149], off
	s_add_i32 m0, s20, 0x2000
	s_add_u32 s16, s16, 0x40080
	v_lshl_add_u64 v[148:149], v[152:153], 0, s[90:91]
	s_addc_u32 s17, s17, 0
	s_add_i32 s20, s46, s24
	global_load_lds_dwordx4 v[148:149], off
	v_lshl_add_u64 v[148:149], s[16:17], 0, v[134:135]
	s_mov_b32 m0, s20
	s_nop 0
	global_load_lds_dwordx4 v[148:149], off
	v_lshl_add_u64 v[148:149], s[16:17], 0, v[130:131]
	s_add_i32 m0, s20, 0x2000
	s_nop 0
	global_load_lds_dwordx4 v[148:149], off
	v_lshl_add_u64 v[148:149], v[156:157], 0, s[90:91]
	s_mov_b32 m0, s31
	s_nop 0
	global_load_lds_dwordx4 v[148:149], off
	v_lshl_add_u64 v[148:149], v[220:221], 0, s[90:91]
	s_mov_b32 m0, s33
	s_nop 0
	global_load_lds_dwordx4 v[148:149], off
	s_waitcnt vmcnt(8)
	s_waitcnt lgkmcnt(0)
	s_barrier
	s_setprio 1
	s_waitcnt lgkmcnt(0)
	v_mfma_f32_16x16x32_bf16 v[62:65], v[144:147], v[188:191], v[62:65]
	v_mfma_f32_16x16x32_bf16 v[58:61], v[164:167], v[188:191], v[58:61]
	v_mfma_f32_16x16x32_bf16 v[46:49], v[144:147], v[196:199], v[46:49]
	v_mfma_f32_16x16x32_bf16 v[42:45], v[164:167], v[196:199], v[42:45]
	v_mfma_f32_16x16x32_bf16 v[30:33], v[144:147], v[204:207], v[30:33]
	v_mfma_f32_16x16x32_bf16 v[26:29], v[164:167], v[204:207], v[26:29]
	v_mfma_f32_16x16x32_bf16 v[14:17], v[144:147], v[212:215], v[14:17]
	v_mfma_f32_16x16x32_bf16 v[10:13], v[164:167], v[212:215], v[10:13]
	v_mfma_f32_16x16x32_bf16 v[62:65], v[160:163], v[192:195], v[62:65]
	v_mfma_f32_16x16x32_bf16 v[58:61], v[168:171], v[192:195], v[58:61]
	v_mfma_f32_16x16x32_bf16 v[46:49], v[160:163], v[200:203], v[46:49]
	v_mfma_f32_16x16x32_bf16 v[42:45], v[168:171], v[200:203], v[42:45]
	v_mfma_f32_16x16x32_bf16 v[30:33], v[160:163], v[208:211], v[30:33]
	v_mfma_f32_16x16x32_bf16 v[26:29], v[168:171], v[208:211], v[26:29]
	v_mfma_f32_16x16x32_bf16 v[14:17], v[160:163], v[216:219], v[14:17]
	v_mfma_f32_16x16x32_bf16 v[10:13], v[168:171], v[216:219], v[10:13]
	s_setprio 0
	s_setprio 1
	v_mfma_f32_16x16x32_bf16 v[54:57], v[172:175], v[188:191], v[54:57]
	v_mfma_f32_16x16x32_bf16 v[50:53], v[180:183], v[188:191], v[50:53]
	v_mfma_f32_16x16x32_bf16 v[38:41], v[172:175], v[196:199], v[38:41]
	v_mfma_f32_16x16x32_bf16 v[34:37], v[180:183], v[196:199], v[34:37]
	v_mfma_f32_16x16x32_bf16 v[22:25], v[172:175], v[204:207], v[22:25]
	v_mfma_f32_16x16x32_bf16 v[18:21], v[180:183], v[204:207], v[18:21]
	v_mfma_f32_16x16x32_bf16 v[6:9], v[172:175], v[212:215], v[6:9]
	v_mfma_f32_16x16x32_bf16 v[2:5], v[180:183], v[212:215], v[2:5]
	v_mfma_f32_16x16x32_bf16 v[54:57], v[176:179], v[192:195], v[54:57]
	v_mfma_f32_16x16x32_bf16 v[50:53], v[184:187], v[192:195], v[50:53]
	v_mfma_f32_16x16x32_bf16 v[38:41], v[176:179], v[200:203], v[38:41]
	v_mfma_f32_16x16x32_bf16 v[34:37], v[184:187], v[200:203], v[34:37]
	v_mfma_f32_16x16x32_bf16 v[22:25], v[176:179], v[208:211], v[22:25]
	v_mfma_f32_16x16x32_bf16 v[18:21], v[184:187], v[208:211], v[18:21]
	v_mfma_f32_16x16x32_bf16 v[6:9], v[176:179], v[216:219], v[6:9]
	v_mfma_f32_16x16x32_bf16 v[2:5], v[184:187], v[216:219], v[2:5]
	s_setprio 0
	s_barrier
	s_add_i32 s44, s44, 2
	s_add_u32 s42, s42, 0x100
	s_addc_u32 s43, s43, 0
	s_add_u32 s14, s14, 0x100
	s_addc_u32 s15, s15, 0

.LBB0_391:
	s_lshl_b32 s20, s42, 8
	s_ashr_i32 s21, s20, 31
	s_lshl_b64 s[20:21], s[20:21], 11
	s_add_u32 s20, s18, s20
	s_addc_u32 s21, s19, s21
	s_and_b64 s[22:23], s[4:5], exec
	s_cselect_b32 s45, s21, s25
	s_cselect_b32 s46, s20, s24
	s_lshl_b32 s22, s41, 8
	s_ashr_i32 s23, s22, 31
	s_lshl_b64 s[22:23], s[22:23], 11
	s_add_u32 s22, s29, s22
	s_addc_u32 s23, s30, s23
	s_and_b64 s[26:27], s[4:5], exec
	s_cselect_b32 s47, s23, s7
	s_cselect_b32 s48, s22, s6
	s_add_u32 s49, s6, 0x100
	s_addc_u32 s50, s7, 0
	s_add_u32 s6, s24, 0x40080
	s_addc_u32 s7, s25, 0
	s_mov_b32 s51, -2
	s_waitcnt vmcnt(0)
	s_add_u32 s24, s6, 0xfffc0080
	s_addc_u32 s25, s7, -1
	s_add_i32 s52, 0, 0x10000
	s_cmp_eq_u32 s51, 12
	s_cselect_b32 s27, s45, s25
	s_cselect_b32 s26, s46, s24
	s_cselect_b32 s25, s47, s50
	s_cselect_b32 s24, s48, s49
	s_add_i32 s54, 0, 0x14000
	v_add_u32_e32 v142, s52, v244
	v_add_u32_e32 v158, s54, v244
	ds_read_b128 v[130:133], v142
	ds_read_b128 v[134:137], v142 offset:1024
	ds_read_b128 v[138:141], v142 offset:2048
	ds_read_b128 v[142:145], v142 offset:3072
	ds_read_b128 v[146:149], v158
	ds_read_b128 v[150:153], v158 offset:1024
	ds_read_b128 v[154:157], v158 offset:2048
	ds_read_b128 v[158:161], v158 offset:3072
	v_lshl_add_u64 v[194:195], s[6:7], 0, v[212:213]
	s_add_i32 m0, s31, 0xc000
	ds_read_b128 v[162:165], v246
	ds_read_b128 v[166:169], v246 offset:1024
	ds_read_b128 v[170:173], v246 offset:2048
	ds_read_b128 v[174:177], v246 offset:3072
	ds_read_b128 v[178:181], v246 offset:4096
	ds_read_b128 v[182:185], v246 offset:5120
	ds_read_b128 v[186:189], v246 offset:6144
	ds_read_b128 v[190:193], v246 offset:7168
	global_load_lds_dwordx4 v[194:195], off
	v_lshl_add_u64 v[194:195], s[6:7], 0, v[210:211]
	s_add_i32 m0, s31, 0xe000
	s_nop 0
	global_load_lds_dwordx4 v[194:195], off
	s_waitcnt vmcnt(8)
	s_waitcnt lgkmcnt(0)
	s_barrier
	s_setprio 1
	s_waitcnt lgkmcnt(0)
	v_mfma_f32_16x16x32_bf16 v[126:129], v[130:133], v[162:165], 0
	v_mfma_f32_16x16x32_bf16 v[122:125], v[138:141], v[162:165], 0
	v_mfma_f32_16x16x32_bf16 v[110:113], v[130:133], v[170:173], 0
	v_mfma_f32_16x16x32_bf16 v[106:109], v[138:141], v[170:173], 0
	v_mfma_f32_16x16x32_bf16 v[94:97], v[130:133], v[178:181], 0
	v_mfma_f32_16x16x32_bf16 v[90:93], v[138:141], v[178:181], 0
	v_mfma_f32_16x16x32_bf16 v[78:81], v[130:133], v[186:189], 0
	v_mfma_f32_16x16x32_bf16 v[74:77], v[138:141], v[186:189], 0
	v_mfma_f32_16x16x32_bf16 v[126:129], v[134:137], v[166:169], v[126:129]
	v_mfma_f32_16x16x32_bf16 v[122:125], v[142:145], v[166:169], v[122:125]
	v_mfma_f32_16x16x32_bf16 v[110:113], v[134:137], v[174:177], v[110:113]
	v_mfma_f32_16x16x32_bf16 v[106:109], v[142:145], v[174:177], v[106:109]
	v_mfma_f32_16x16x32_bf16 v[94:97], v[134:137], v[182:185], v[94:97]
	v_mfma_f32_16x16x32_bf16 v[90:93], v[142:145], v[182:185], v[90:93]
	v_mfma_f32_16x16x32_bf16 v[78:81], v[134:137], v[190:193], v[78:81]
	v_mfma_f32_16x16x32_bf16 v[74:77], v[142:145], v[190:193], v[74:77]
	s_setprio 0
	s_setprio 1
	v_mfma_f32_16x16x32_bf16 v[118:121], v[146:149], v[162:165], 0
	v_mfma_f32_16x16x32_bf16 v[114:117], v[154:157], v[162:165], 0
	v_mfma_f32_16x16x32_bf16 v[102:105], v[146:149], v[170:173], 0
	v_mfma_f32_16x16x32_bf16 v[98:101], v[154:157], v[170:173], 0
	v_mfma_f32_16x16x32_bf16 v[86:89], v[146:149], v[178:181], 0
	v_mfma_f32_16x16x32_bf16 v[82:85], v[154:157], v[178:181], 0
	v_mfma_f32_16x16x32_bf16 v[70:73], v[146:149], v[186:189], 0
	v_mfma_f32_16x16x32_bf16 v[66:69], v[154:157], v[186:189], 0
	v_mfma_f32_16x16x32_bf16 v[118:121], v[150:153], v[166:169], v[118:121]
	v_mfma_f32_16x16x32_bf16 v[114:117], v[158:161], v[166:169], v[114:117]
	v_mfma_f32_16x16x32_bf16 v[102:105], v[150:153], v[174:177], v[102:105]
	v_mfma_f32_16x16x32_bf16 v[98:101], v[158:161], v[174:177], v[98:101]
	v_mfma_f32_16x16x32_bf16 v[86:89], v[150:153], v[182:185], v[86:89]
	v_mfma_f32_16x16x32_bf16 v[82:85], v[158:161], v[182:185], v[82:85]
	v_mfma_f32_16x16x32_bf16 v[70:73], v[150:153], v[190:193], v[70:73]
	v_mfma_f32_16x16x32_bf16 v[66:69], v[158:161], v[190:193], v[66:69]
	s_setprio 0
	s_barrier
	s_add_i32 s52, s52, s28
	v_lshl_add_u64 v[194:195], s[24:25], 0, v[204:205]
	s_mov_b32 m0, s52
	ds_read_b128 v[162:165], v246 offset:16384
	ds_read_b128 v[166:169], v246 offset:17408
	ds_read_b128 v[170:173], v246 offset:18432
	ds_read_b128 v[174:177], v246 offset:19456
	ds_read_b128 v[178:181], v246 offset:20480
	ds_read_b128 v[182:185], v246 offset:21504
	ds_read_b128 v[186:189], v246 offset:22528
	ds_read_b128 v[190:193], v246 offset:23552
	global_load_lds_dwordx4 v[194:195], off
	s_add_i32 m0, s52, 0x2000
	s_add_u32 s52, s24, 0x40000
	v_lshl_add_u64 v[196:197], s[24:25], 0, v[208:209]
	s_addc_u32 s53, s25, 0
	s_add_i32 s54, s54, s28
	global_load_lds_dwordx4 v[196:197], off
	v_lshl_add_u64 v[198:199], s[52:53], 0, v[204:205]
	s_mov_b32 m0, s54
	v_lshl_add_u64 v[200:201], s[26:27], 0, v[206:207]
	global_load_lds_dwordx4 v[198:199], off
	v_lshl_add_u64 v[198:199], s[52:53], 0, v[208:209]
	s_add_i32 m0, s54, 0x2000
	s_nop 0
	global_load_lds_dwordx4 v[198:199], off
	v_lshl_add_u64 v[198:199], s[26:27], 0, v[202:203]
	s_mov_b32 m0, s31
	s_nop 0
	global_load_lds_dwordx4 v[198:199], off
	s_mov_b32 m0, s34
	s_nop 0
	global_load_lds_dwordx4 v[200:201], off
	s_waitcnt vmcnt(8)
	s_waitcnt lgkmcnt(0)
	s_barrier
	s_setprio 1
	s_waitcnt lgkmcnt(0)
	v_mfma_f32_16x16x32_bf16 v[62:65], v[130:133], v[162:165], 0
	v_mfma_f32_16x16x32_bf16 v[58:61], v[138:141], v[162:165], 0
	v_mfma_f32_16x16x32_bf16 v[46:49], v[130:133], v[170:173], 0
	v_mfma_f32_16x16x32_bf16 v[42:45], v[138:141], v[170:173], 0
	v_mfma_f32_16x16x32_bf16 v[30:33], v[130:133], v[178:181], 0
	v_mfma_f32_16x16x32_bf16 v[26:29], v[138:141], v[178:181], 0
	v_mfma_f32_16x16x32_bf16 v[14:17], v[130:133], v[186:189], 0
	v_mfma_f32_16x16x32_bf16 v[10:13], v[138:141], v[186:189], 0
	v_mfma_f32_16x16x32_bf16 v[62:65], v[134:137], v[166:169], v[62:65]
	v_mfma_f32_16x16x32_bf16 v[58:61], v[142:145], v[166:169], v[58:61]
	v_mfma_f32_16x16x32_bf16 v[46:49], v[134:137], v[174:177], v[46:49]
	v_mfma_f32_16x16x32_bf16 v[42:45], v[142:145], v[174:177], v[42:45]
	v_mfma_f32_16x16x32_bf16 v[30:33], v[134:137], v[182:185], v[30:33]
	v_mfma_f32_16x16x32_bf16 v[26:29], v[142:145], v[182:185], v[26:29]
	v_mfma_f32_16x16x32_bf16 v[14:17], v[134:137], v[190:193], v[14:17]
	v_mfma_f32_16x16x32_bf16 v[10:13], v[142:145], v[190:193], v[10:13]
	s_setprio 0
	s_setprio 1
	v_mfma_f32_16x16x32_bf16 v[54:57], v[146:149], v[162:165], 0
	v_mfma_f32_16x16x32_bf16 v[50:53], v[154:157], v[162:165], 0
	v_mfma_f32_16x16x32_bf16 v[38:41], v[146:149], v[170:173], 0
	v_mfma_f32_16x16x32_bf16 v[34:37], v[154:157], v[170:173], 0
	v_mfma_f32_16x16x32_bf16 v[22:25], v[146:149], v[178:181], 0
	v_mfma_f32_16x16x32_bf16 v[18:21], v[154:157], v[178:181], 0
	v_mfma_f32_16x16x32_bf16 v[6:9], v[146:149], v[186:189], 0
	v_mfma_f32_16x16x32_bf16 v[2:5], v[154:157], v[186:189], 0
	v_mfma_f32_16x16x32_bf16 v[54:57], v[150:153], v[166:169], v[54:57]
	v_mfma_f32_16x16x32_bf16 v[50:53], v[158:161], v[166:169], v[50:53]
	v_mfma_f32_16x16x32_bf16 v[38:41], v[150:153], v[174:177], v[38:41]
	v_mfma_f32_16x16x32_bf16 v[34:37], v[158:161], v[174:177], v[34:37]
	v_mfma_f32_16x16x32_bf16 v[22:25], v[150:153], v[182:185], v[22:25]
	v_mfma_f32_16x16x32_bf16 v[18:21], v[158:161], v[182:185], v[18:21]
	v_mfma_f32_16x16x32_bf16 v[6:9], v[150:153], v[190:193], v[6:9]
	v_mfma_f32_16x16x32_bf16 v[2:5], v[158:161], v[190:193], v[2:5]
	s_setprio 0
	s_barrier
	s_add_i32 s52, 0, 0x18000
	s_add_i32 s53, 0, 0x1c000
	v_add_u32_e32 v142, s52, v244
	v_add_u32_e32 v158, s53, v244
	ds_read_b128 v[130:133], v142
	ds_read_b128 v[134:137], v142 offset:1024
	ds_read_b128 v[138:141], v142 offset:2048
	ds_read_b128 v[142:145], v142 offset:3072
	ds_read_b128 v[146:149], v158
	ds_read_b128 v[150:153], v158 offset:1024
	ds_read_b128 v[154:157], v158 offset:2048
	ds_read_b128 v[158:161], v158 offset:3072
	s_add_u32 s26, s26, 0x40000
	s_addc_u32 s27, s27, 0
	s_mov_b32 m0, s35
	v_lshl_add_u64 v[214:215], s[26:27], 0, v[202:203]
	ds_read_b128 v[162:165], v246 offset:32768
	ds_read_b128 v[166:169], v246 offset:33792
	ds_read_b128 v[170:173], v246 offset:34816
	ds_read_b128 v[174:177], v246 offset:35840
	ds_read_b128 v[178:181], v246 offset:36864
	ds_read_b128 v[182:185], v246 offset:37888
	ds_read_b128 v[186:189], v246 offset:38912
	ds_read_b128 v[190:193], v246 offset:39936
	global_load_lds_dwordx4 v[214:215], off
	v_lshl_add_u64 v[214:215], s[26:27], 0, v[206:207]
	s_mov_b32 m0, s36
	s_nop 0
	global_load_lds_dwordx4 v[214:215], off
	s_waitcnt vmcnt(8)
	s_waitcnt lgkmcnt(0)
	s_barrier
	s_setprio 1
	s_waitcnt lgkmcnt(0)
	v_mfma_f32_16x16x32_bf16 v[126:129], v[130:133], v[162:165], v[126:129]
	v_mfma_f32_16x16x32_bf16 v[122:125], v[138:141], v[162:165], v[122:125]
	v_mfma_f32_16x16x32_bf16 v[110:113], v[130:133], v[170:173], v[110:113]
	v_mfma_f32_16x16x32_bf16 v[106:109], v[138:141], v[170:173], v[106:109]
	v_mfma_f32_16x16x32_bf16 v[94:97], v[130:133], v[178:181], v[94:97]
	v_mfma_f32_16x16x32_bf16 v[90:93], v[138:141], v[178:181], v[90:93]
	v_mfma_f32_16x16x32_bf16 v[78:81], v[130:133], v[186:189], v[78:81]
	v_mfma_f32_16x16x32_bf16 v[74:77], v[138:141], v[186:189], v[74:77]
	v_mfma_f32_16x16x32_bf16 v[126:129], v[134:137], v[166:169], v[126:129]
	v_mfma_f32_16x16x32_bf16 v[122:125], v[142:145], v[166:169], v[122:125]
	v_mfma_f32_16x16x32_bf16 v[110:113], v[134:137], v[174:177], v[110:113]
	v_mfma_f32_16x16x32_bf16 v[106:109], v[142:145], v[174:177], v[106:109]
	v_mfma_f32_16x16x32_bf16 v[94:97], v[134:137], v[182:185], v[94:97]
	v_mfma_f32_16x16x32_bf16 v[90:93], v[142:145], v[182:185], v[90:93]
	v_mfma_f32_16x16x32_bf16 v[78:81], v[134:137], v[190:193], v[78:81]
	v_mfma_f32_16x16x32_bf16 v[74:77], v[142:145], v[190:193], v[74:77]
	s_setprio 0
	s_setprio 1
	v_mfma_f32_16x16x32_bf16 v[118:121], v[146:149], v[162:165], v[118:121]
	v_mfma_f32_16x16x32_bf16 v[114:117], v[154:157], v[162:165], v[114:117]
	v_mfma_f32_16x16x32_bf16 v[102:105], v[146:149], v[170:173], v[102:105]
	v_mfma_f32_16x16x32_bf16 v[98:101], v[154:157], v[170:173], v[98:101]
	v_mfma_f32_16x16x32_bf16 v[86:89], v[146:149], v[178:181], v[86:89]
	v_mfma_f32_16x16x32_bf16 v[82:85], v[154:157], v[178:181], v[82:85]
	v_mfma_f32_16x16x32_bf16 v[70:73], v[146:149], v[186:189], v[70:73]
	v_mfma_f32_16x16x32_bf16 v[66:69], v[154:157], v[186:189], v[66:69]
	v_mfma_f32_16x16x32_bf16 v[118:121], v[150:153], v[166:169], v[118:121]
	v_mfma_f32_16x16x32_bf16 v[114:117], v[158:161], v[166:169], v[114:117]
	v_mfma_f32_16x16x32_bf16 v[102:105], v[150:153], v[174:177], v[102:105]
	v_mfma_f32_16x16x32_bf16 v[98:101], v[158:161], v[174:177], v[98:101]
	v_mfma_f32_16x16x32_bf16 v[86:89], v[150:153], v[182:185], v[86:89]
	v_mfma_f32_16x16x32_bf16 v[82:85], v[158:161], v[182:185], v[82:85]
	v_mfma_f32_16x16x32_bf16 v[70:73], v[150:153], v[190:193], v[70:73]
	v_mfma_f32_16x16x32_bf16 v[66:69], v[158:161], v[190:193], v[66:69]
	s_setprio 0
	s_barrier
	s_add_i32 s26, s52, s28
	v_lshl_add_u64 v[194:195], v[194:195], 0, s[90:91]
	s_mov_b32 m0, s26
	ds_read_b128 v[162:165], v246 offset:49152
	ds_read_b128 v[166:169], v246 offset:50176
	ds_read_b128 v[170:173], v246 offset:51200
	ds_read_b128 v[174:177], v246 offset:52224
	ds_read_b128 v[178:181], v246 offset:53248
	ds_read_b128 v[182:185], v246 offset:54272
	ds_read_b128 v[186:189], v246 offset:55296
	ds_read_b128 v[190:193], v246 offset:56320
	global_load_lds_dwordx4 v[194:195], off
	s_add_i32 m0, s26, 0x2000
	s_add_u32 s24, s24, 0x40080
	v_lshl_add_u64 v[194:195], v[196:197], 0, s[90:91]
	s_addc_u32 s25, s25, 0
	s_add_i32 s26, s53, s28
	global_load_lds_dwordx4 v[194:195], off
	v_lshl_add_u64 v[194:195], s[24:25], 0, v[204:205]
	s_mov_b32 m0, s26
	s_nop 0
	global_load_lds_dwordx4 v[194:195], off
	v_lshl_add_u64 v[194:195], s[24:25], 0, v[208:209]
	s_add_i32 m0, s26, 0x2000
	s_nop 0
	global_load_lds_dwordx4 v[194:195], off
	v_lshl_add_u64 v[194:195], v[198:199], 0, s[90:91]
	s_mov_b32 m0, s33
	s_nop 0
	global_load_lds_dwordx4 v[194:195], off
	v_lshl_add_u64 v[194:195], v[200:201], 0, s[90:91]
	s_mov_b32 m0, s38
	s_nop 0
	global_load_lds_dwordx4 v[194:195], off
	s_waitcnt vmcnt(8)
	s_waitcnt lgkmcnt(0)
	s_barrier
	s_setprio 1
	s_waitcnt lgkmcnt(0)
	v_mfma_f32_16x16x32_bf16 v[62:65], v[130:133], v[162:165], v[62:65]
	v_mfma_f32_16x16x32_bf16 v[58:61], v[138:141], v[162:165], v[58:61]
	v_mfma_f32_16x16x32_bf16 v[46:49], v[130:133], v[170:173], v[46:49]
	v_mfma_f32_16x16x32_bf16 v[42:45], v[138:141], v[170:173], v[42:45]
	v_mfma_f32_16x16x32_bf16 v[30:33], v[130:133], v[178:181], v[30:33]
	v_mfma_f32_16x16x32_bf16 v[26:29], v[138:141], v[178:181], v[26:29]
	v_mfma_f32_16x16x32_bf16 v[14:17], v[130:133], v[186:189], v[14:17]
	v_mfma_f32_16x16x32_bf16 v[10:13], v[138:141], v[186:189], v[10:13]
	v_mfma_f32_16x16x32_bf16 v[62:65], v[134:137], v[166:169], v[62:65]
	v_mfma_f32_16x16x32_bf16 v[58:61], v[142:145], v[166:169], v[58:61]
	v_mfma_f32_16x16x32_bf16 v[46:49], v[134:137], v[174:177], v[46:49]
	v_mfma_f32_16x16x32_bf16 v[42:45], v[142:145], v[174:177], v[42:45]
	v_mfma_f32_16x16x32_bf16 v[30:33], v[134:137], v[182:185], v[30:33]
	v_mfma_f32_16x16x32_bf16 v[26:29], v[142:145], v[182:185], v[26:29]
	v_mfma_f32_16x16x32_bf16 v[14:17], v[134:137], v[190:193], v[14:17]
	v_mfma_f32_16x16x32_bf16 v[10:13], v[142:145], v[190:193], v[10:13]
	s_setprio 0
	s_setprio 1
	v_mfma_f32_16x16x32_bf16 v[54:57], v[146:149], v[162:165], v[54:57]
	v_mfma_f32_16x16x32_bf16 v[50:53], v[154:157], v[162:165], v[50:53]
	v_mfma_f32_16x16x32_bf16 v[38:41], v[146:149], v[170:173], v[38:41]
	v_mfma_f32_16x16x32_bf16 v[34:37], v[154:157], v[170:173], v[34:37]
	v_mfma_f32_16x16x32_bf16 v[22:25], v[146:149], v[178:181], v[22:25]
	v_mfma_f32_16x16x32_bf16 v[18:21], v[154:157], v[178:181], v[18:21]
	v_mfma_f32_16x16x32_bf16 v[6:9], v[146:149], v[186:189], v[6:9]
	v_mfma_f32_16x16x32_bf16 v[2:5], v[154:157], v[186:189], v[2:5]
	v_mfma_f32_16x16x32_bf16 v[54:57], v[150:153], v[166:169], v[54:57]
	v_mfma_f32_16x16x32_bf16 v[50:53], v[158:161], v[166:169], v[50:53]
	v_mfma_f32_16x16x32_bf16 v[38:41], v[150:153], v[174:177], v[38:41]
	v_mfma_f32_16x16x32_bf16 v[34:37], v[158:161], v[174:177], v[34:37]
	v_mfma_f32_16x16x32_bf16 v[22:25], v[150:153], v[182:185], v[22:25]
	v_mfma_f32_16x16x32_bf16 v[18:21], v[158:161], v[182:185], v[18:21]
	v_mfma_f32_16x16x32_bf16 v[6:9], v[150:153], v[190:193], v[6:9]
	v_mfma_f32_16x16x32_bf16 v[2:5], v[158:161], v[190:193], v[2:5]
	s_setprio 0
	s_barrier
	s_add_i32 s51, s51, 2
	s_add_u32 s49, s49, 0x100
	s_addc_u32 s50, s50, 0
	s_add_u32 s6, s6, 0x100
	s_addc_u32 s7, s7, 0

.LBB0_673:
	s_lshl_b32 s16, s38, 8
	s_ashr_i32 s17, s16, 31
	s_lshl_b64 s[16:17], s[16:17], 11
	s_add_u32 s16, s23, s16
	s_addc_u32 s17, s24, s17
	s_and_b64 s[4:5], s[4:5], exec
	s_cselect_b32 s41, s17, s21
	s_cselect_b32 s42, s16, s20
	s_add_u32 s43, s18, 0x100
	s_addc_u32 s44, s19, 0
	s_add_u32 s4, s20, 0x40080
	s_addc_u32 s5, s21, 0
	s_mov_b32 s20, -2
	s_add_u32 s18, s4, 0xfffc0080
	s_addc_u32 s19, s5, -1
	s_add_i32 s21, 0, 0x10000
	s_cmp_eq_u32 s20, 12
	s_cselect_b32 s19, s41, s19
	s_cselect_b32 s18, s42, s18
	v_add_u32_e32 v155, s21, v153
	s_cselect_b32 s47, s15, s44
	s_cselect_b32 s46, s14, s43
	s_add_i32 s45, 0, 0x14000
	ds_read_b128 v[122:125], v155
	ds_read_b128 v[134:137], v155 offset:1024
	ds_read_b128 v[148:151], v155 offset:2048
	ds_read_b128 v[156:159], v155 offset:3072
	v_add_u32_e32 v155, s45, v153
	ds_read_b128 v[160:163], v155
	ds_read_b128 v[164:167], v155 offset:1024
	ds_read_b128 v[168:171], v155 offset:2048
	ds_read_b128 v[172:175], v155 offset:3072
	v_lshl_add_u64 v[192:193], s[4:5], 0, v[146:147]
	s_add_i32 m0, s27, 0xc000
	ds_read_b128 v[176:179], v1
	ds_read_b128 v[180:183], v1 offset:1024
	ds_read_b128 v[184:187], v1 offset:2048
	ds_read_b128 v[188:191], v1 offset:3072
	ds_read_b128 v[202:205], v1 offset:4096
	ds_read_b128 v[206:209], v1 offset:5120
	ds_read_b128 v[210:213], v1 offset:6144
	ds_read_b128 v[214:217], v1 offset:7168
	global_load_lds_dwordx4 v[192:193], off
	v_lshl_add_u64 v[192:193], s[4:5], 0, v[142:143]
	s_add_i32 m0, s27, 0xe000
	s_nop 0
	global_load_lds_dwordx4 v[192:193], off
	s_waitcnt vmcnt(8)
	s_waitcnt lgkmcnt(0)
	s_barrier
	s_setprio 1
	s_waitcnt lgkmcnt(0)
	v_mfma_f32_16x16x32_bf16 v[130:133], v[122:125], v[176:179], 0
	v_mfma_f32_16x16x32_bf16 v[126:129], v[148:151], v[176:179], 0
	v_mfma_f32_16x16x32_bf16 v[118:121], v[122:125], v[184:187], 0
	v_mfma_f32_16x16x32_bf16 v[114:117], v[148:151], v[184:187], 0
	v_mfma_f32_16x16x32_bf16 v[110:113], v[122:125], v[202:205], 0
	v_mfma_f32_16x16x32_bf16 v[106:109], v[148:151], v[202:205], 0
	v_mfma_f32_16x16x32_bf16 v[102:105], v[122:125], v[210:213], 0
	v_mfma_f32_16x16x32_bf16 v[98:101], v[148:151], v[210:213], 0
	v_mfma_f32_16x16x32_bf16 v[130:133], v[134:137], v[180:183], v[130:133]
	v_mfma_f32_16x16x32_bf16 v[126:129], v[156:159], v[180:183], v[126:129]
	v_mfma_f32_16x16x32_bf16 v[118:121], v[134:137], v[188:191], v[118:121]
	v_mfma_f32_16x16x32_bf16 v[114:117], v[156:159], v[188:191], v[114:117]
	v_mfma_f32_16x16x32_bf16 v[110:113], v[134:137], v[206:209], v[110:113]
	v_mfma_f32_16x16x32_bf16 v[106:109], v[156:159], v[206:209], v[106:109]
	v_mfma_f32_16x16x32_bf16 v[102:105], v[134:137], v[214:217], v[102:105]
	v_mfma_f32_16x16x32_bf16 v[98:101], v[156:159], v[214:217], v[98:101]
	s_setprio 0
	s_setprio 1
	v_mfma_f32_16x16x32_bf16 v[74:77], v[160:163], v[176:179], 0
	v_mfma_f32_16x16x32_bf16 v[66:69], v[168:171], v[176:179], 0
	v_mfma_f32_16x16x32_bf16 v[54:57], v[160:163], v[184:187], 0
	v_mfma_f32_16x16x32_bf16 v[50:53], v[168:171], v[184:187], 0
	v_mfma_f32_16x16x32_bf16 v[46:49], v[160:163], v[202:205], 0
	v_mfma_f32_16x16x32_bf16 v[42:45], v[168:171], v[202:205], 0
	v_mfma_f32_16x16x32_bf16 v[38:41], v[160:163], v[210:213], 0
	v_mfma_f32_16x16x32_bf16 v[34:37], v[168:171], v[210:213], 0
	v_mfma_f32_16x16x32_bf16 v[74:77], v[164:167], v[180:183], v[74:77]
	v_mfma_f32_16x16x32_bf16 v[66:69], v[172:175], v[180:183], v[66:69]
	v_mfma_f32_16x16x32_bf16 v[54:57], v[164:167], v[188:191], v[54:57]
	v_mfma_f32_16x16x32_bf16 v[50:53], v[172:175], v[188:191], v[50:53]
	v_mfma_f32_16x16x32_bf16 v[46:49], v[164:167], v[206:209], v[46:49]
	v_mfma_f32_16x16x32_bf16 v[42:45], v[172:175], v[206:209], v[42:45]
	v_mfma_f32_16x16x32_bf16 v[38:41], v[164:167], v[214:217], v[38:41]
	v_mfma_f32_16x16x32_bf16 v[34:37], v[172:175], v[214:217], v[34:37]
	s_setprio 0
	s_barrier
	s_add_i32 s21, s21, s25
	v_lshl_add_u64 v[192:193], s[46:47], 0, v[140:141]
	s_mov_b32 m0, s21
	ds_read_b128 v[176:179], v1 offset:16384
	ds_read_b128 v[180:183], v1 offset:17408
	ds_read_b128 v[184:187], v1 offset:18432
	ds_read_b128 v[188:191], v1 offset:19456
	ds_read_b128 v[202:205], v1 offset:20480
	ds_read_b128 v[206:209], v1 offset:21504
	ds_read_b128 v[210:213], v1 offset:22528
	ds_read_b128 v[214:217], v1 offset:23552
	global_load_lds_dwordx4 v[192:193], off
	s_add_i32 m0, s21, 0x2000
	v_lshl_add_u64 v[194:195], s[46:47], 0, v[144:145]
	s_add_u32 s46, s46, s10
	s_addc_u32 s47, s47, s11
	s_add_i32 s21, s45, s25
	global_load_lds_dwordx4 v[194:195], off
	v_lshl_add_u64 v[196:197], s[46:47], 0, v[140:141]
	s_mov_b32 m0, s21
	v_lshl_add_u64 v[198:199], s[46:47], 0, v[144:145]
	global_load_lds_dwordx4 v[196:197], off
	s_add_i32 m0, s21, 0x2000
	v_lshl_add_u64 v[200:201], s[18:19], 0, v[138:139]
	global_load_lds_dwordx4 v[198:199], off
	s_mov_b32 m0, s27
	v_lshl_add_u64 v[218:219], s[18:19], 0, v[142:143]
	global_load_lds_dwordx4 v[200:201], off
	s_mov_b32 m0, s28
	s_nop 0
	global_load_lds_dwordx4 v[218:219], off
	s_waitcnt vmcnt(8)
	s_waitcnt lgkmcnt(0)
	s_barrier
	s_setprio 1
	s_waitcnt lgkmcnt(0)
	v_mfma_f32_16x16x32_bf16 v[94:97], v[122:125], v[176:179], 0
	v_mfma_f32_16x16x32_bf16 v[90:93], v[148:151], v[176:179], 0
	v_mfma_f32_16x16x32_bf16 v[86:89], v[122:125], v[184:187], 0
	v_mfma_f32_16x16x32_bf16 v[82:85], v[148:151], v[184:187], 0
	v_mfma_f32_16x16x32_bf16 v[78:81], v[122:125], v[202:205], 0
	v_mfma_f32_16x16x32_bf16 v[70:73], v[148:151], v[202:205], 0
	v_mfma_f32_16x16x32_bf16 v[62:65], v[122:125], v[210:213], 0
	v_mfma_f32_16x16x32_bf16 v[58:61], v[148:151], v[210:213], 0
	v_mfma_f32_16x16x32_bf16 v[94:97], v[134:137], v[180:183], v[94:97]
	v_mfma_f32_16x16x32_bf16 v[90:93], v[156:159], v[180:183], v[90:93]
	v_mfma_f32_16x16x32_bf16 v[86:89], v[134:137], v[188:191], v[86:89]
	v_mfma_f32_16x16x32_bf16 v[82:85], v[156:159], v[188:191], v[82:85]
	v_mfma_f32_16x16x32_bf16 v[78:81], v[134:137], v[206:209], v[78:81]
	v_mfma_f32_16x16x32_bf16 v[70:73], v[156:159], v[206:209], v[70:73]
	v_mfma_f32_16x16x32_bf16 v[62:65], v[134:137], v[214:217], v[62:65]
	v_mfma_f32_16x16x32_bf16 v[58:61], v[156:159], v[214:217], v[58:61]
	s_setprio 0
	s_setprio 1
	v_mfma_f32_16x16x32_bf16 v[30:33], v[160:163], v[176:179], 0
	v_mfma_f32_16x16x32_bf16 v[26:29], v[168:171], v[176:179], 0
	v_mfma_f32_16x16x32_bf16 v[22:25], v[160:163], v[184:187], 0
	v_mfma_f32_16x16x32_bf16 v[18:21], v[168:171], v[184:187], 0
	v_mfma_f32_16x16x32_bf16 v[14:17], v[160:163], v[202:205], 0
	v_mfma_f32_16x16x32_bf16 v[10:13], v[168:171], v[202:205], 0
	v_mfma_f32_16x16x32_bf16 v[6:9], v[160:163], v[210:213], 0
	v_mfma_f32_16x16x32_bf16 v[2:5], v[168:171], v[210:213], 0
	v_mfma_f32_16x16x32_bf16 v[30:33], v[164:167], v[180:183], v[30:33]
	v_mfma_f32_16x16x32_bf16 v[26:29], v[172:175], v[180:183], v[26:29]
	v_mfma_f32_16x16x32_bf16 v[22:25], v[164:167], v[188:191], v[22:25]
	v_mfma_f32_16x16x32_bf16 v[18:21], v[172:175], v[188:191], v[18:21]
	v_mfma_f32_16x16x32_bf16 v[14:17], v[164:167], v[206:209], v[14:17]
	v_mfma_f32_16x16x32_bf16 v[10:13], v[172:175], v[206:209], v[10:13]
	v_mfma_f32_16x16x32_bf16 v[6:9], v[164:167], v[214:217], v[6:9]
	v_mfma_f32_16x16x32_bf16 v[2:5], v[172:175], v[214:217], v[2:5]
	s_setprio 0
	s_barrier
	s_add_i32 s21, 0, 0x18000
	v_add_u32_e32 v155, s21, v153
	s_add_i32 s45, 0, 0x1c000
	ds_read_b128 v[122:125], v155
	ds_read_b128 v[134:137], v155 offset:1024
	ds_read_b128 v[148:151], v155 offset:2048
	ds_read_b128 v[156:159], v155 offset:3072
	v_add_u32_e32 v155, s45, v153
	ds_read_b128 v[160:163], v155
	ds_read_b128 v[164:167], v155 offset:1024
	ds_read_b128 v[168:171], v155 offset:2048
	ds_read_b128 v[172:175], v155 offset:3072
	s_add_u32 s18, s18, 0x40000
	s_addc_u32 s19, s19, 0
	s_mov_b32 m0, s29
	v_lshl_add_u64 v[220:221], s[18:19], 0, v[138:139]
	ds_read_b128 v[176:179], v1 offset:32768
	ds_read_b128 v[180:183], v1 offset:33792
	ds_read_b128 v[184:187], v1 offset:34816
	ds_read_b128 v[188:191], v1 offset:35840
	ds_read_b128 v[202:205], v1 offset:36864
	ds_read_b128 v[206:209], v1 offset:37888
	ds_read_b128 v[210:213], v1 offset:38912
	ds_read_b128 v[214:217], v1 offset:39936
	global_load_lds_dwordx4 v[220:221], off
	v_lshl_add_u64 v[220:221], s[18:19], 0, v[142:143]
	s_mov_b32 m0, s31
	s_nop 0
	global_load_lds_dwordx4 v[220:221], off
	s_waitcnt vmcnt(8)
	s_waitcnt lgkmcnt(0)
	s_barrier
	s_setprio 1
	s_waitcnt lgkmcnt(0)
	v_mfma_f32_16x16x32_bf16 v[130:133], v[122:125], v[176:179], v[130:133]
	v_mfma_f32_16x16x32_bf16 v[126:129], v[148:151], v[176:179], v[126:129]
	v_mfma_f32_16x16x32_bf16 v[118:121], v[122:125], v[184:187], v[118:121]
	v_mfma_f32_16x16x32_bf16 v[114:117], v[148:151], v[184:187], v[114:117]
	v_mfma_f32_16x16x32_bf16 v[110:113], v[122:125], v[202:205], v[110:113]
	v_mfma_f32_16x16x32_bf16 v[106:109], v[148:151], v[202:205], v[106:109]
	v_mfma_f32_16x16x32_bf16 v[102:105], v[122:125], v[210:213], v[102:105]
	v_mfma_f32_16x16x32_bf16 v[98:101], v[148:151], v[210:213], v[98:101]
	v_mfma_f32_16x16x32_bf16 v[130:133], v[134:137], v[180:183], v[130:133]
	v_mfma_f32_16x16x32_bf16 v[126:129], v[156:159], v[180:183], v[126:129]
	v_mfma_f32_16x16x32_bf16 v[118:121], v[134:137], v[188:191], v[118:121]
	v_mfma_f32_16x16x32_bf16 v[114:117], v[156:159], v[188:191], v[114:117]
	v_mfma_f32_16x16x32_bf16 v[110:113], v[134:137], v[206:209], v[110:113]
	v_mfma_f32_16x16x32_bf16 v[106:109], v[156:159], v[206:209], v[106:109]
	v_mfma_f32_16x16x32_bf16 v[102:105], v[134:137], v[214:217], v[102:105]
	v_mfma_f32_16x16x32_bf16 v[98:101], v[156:159], v[214:217], v[98:101]
	s_setprio 0
	s_setprio 1
	v_mfma_f32_16x16x32_bf16 v[74:77], v[160:163], v[176:179], v[74:77]
	v_mfma_f32_16x16x32_bf16 v[66:69], v[168:171], v[176:179], v[66:69]
	v_mfma_f32_16x16x32_bf16 v[54:57], v[160:163], v[184:187], v[54:57]
	v_mfma_f32_16x16x32_bf16 v[50:53], v[168:171], v[184:187], v[50:53]
	v_mfma_f32_16x16x32_bf16 v[46:49], v[160:163], v[202:205], v[46:49]
	v_mfma_f32_16x16x32_bf16 v[42:45], v[168:171], v[202:205], v[42:45]
	v_mfma_f32_16x16x32_bf16 v[38:41], v[160:163], v[210:213], v[38:41]
	v_mfma_f32_16x16x32_bf16 v[34:37], v[168:171], v[210:213], v[34:37]
	v_mfma_f32_16x16x32_bf16 v[74:77], v[164:167], v[180:183], v[74:77]
	v_mfma_f32_16x16x32_bf16 v[66:69], v[172:175], v[180:183], v[66:69]
	v_mfma_f32_16x16x32_bf16 v[54:57], v[164:167], v[188:191], v[54:57]
	v_mfma_f32_16x16x32_bf16 v[50:53], v[172:175], v[188:191], v[50:53]
	v_mfma_f32_16x16x32_bf16 v[46:49], v[164:167], v[206:209], v[46:49]
	v_mfma_f32_16x16x32_bf16 v[42:45], v[172:175], v[206:209], v[42:45]
	v_mfma_f32_16x16x32_bf16 v[38:41], v[164:167], v[214:217], v[38:41]
	v_mfma_f32_16x16x32_bf16 v[34:37], v[172:175], v[214:217], v[34:37]
	s_setprio 0
	s_barrier
	s_add_i32 s18, s21, s25
	v_lshl_add_u64 v[192:193], v[192:193], 0, s[90:91]
	s_mov_b32 m0, s18
	ds_read_b128 v[176:179], v1 offset:49152
	ds_read_b128 v[180:183], v1 offset:50176
	ds_read_b128 v[184:187], v1 offset:51200
	ds_read_b128 v[188:191], v1 offset:52224
	ds_read_b128 v[202:205], v1 offset:53248
	ds_read_b128 v[206:209], v1 offset:54272
	ds_read_b128 v[210:213], v1 offset:55296
	ds_read_b128 v[214:217], v1 offset:56320
	global_load_lds_dwordx4 v[192:193], off
	v_lshl_add_u64 v[192:193], v[194:195], 0, s[90:91]
	s_add_i32 m0, s18, 0x2000
	s_add_i32 s18, s45, s25
	global_load_lds_dwordx4 v[192:193], off
	v_lshl_add_u64 v[192:193], v[196:197], 0, s[90:91]
	s_mov_b32 m0, s18
	s_nop 0
	global_load_lds_dwordx4 v[192:193], off
	v_lshl_add_u64 v[192:193], v[198:199], 0, s[90:91]
	s_add_i32 m0, s18, 0x2000
	s_nop 0
	global_load_lds_dwordx4 v[192:193], off
	v_lshl_add_u64 v[192:193], v[200:201], 0, s[90:91]
	s_mov_b32 m0, s33
	s_nop 0
	global_load_lds_dwordx4 v[192:193], off
	v_lshl_add_u64 v[192:193], v[218:219], 0, s[90:91]
	s_mov_b32 m0, s34
	s_nop 0
	global_load_lds_dwordx4 v[192:193], off
	s_waitcnt vmcnt(8)
	s_waitcnt lgkmcnt(0)
	s_barrier
	s_setprio 1
	s_waitcnt lgkmcnt(0)
	v_mfma_f32_16x16x32_bf16 v[94:97], v[122:125], v[176:179], v[94:97]
	v_mfma_f32_16x16x32_bf16 v[90:93], v[148:151], v[176:179], v[90:93]
	v_mfma_f32_16x16x32_bf16 v[86:89], v[122:125], v[184:187], v[86:89]
	v_mfma_f32_16x16x32_bf16 v[82:85], v[148:151], v[184:187], v[82:85]
	v_mfma_f32_16x16x32_bf16 v[78:81], v[122:125], v[202:205], v[78:81]
	v_mfma_f32_16x16x32_bf16 v[70:73], v[148:151], v[202:205], v[70:73]
	v_mfma_f32_16x16x32_bf16 v[62:65], v[122:125], v[210:213], v[62:65]
	v_mfma_f32_16x16x32_bf16 v[58:61], v[148:151], v[210:213], v[58:61]
	v_mfma_f32_16x16x32_bf16 v[94:97], v[134:137], v[180:183], v[94:97]
	v_mfma_f32_16x16x32_bf16 v[90:93], v[156:159], v[180:183], v[90:93]
	v_mfma_f32_16x16x32_bf16 v[86:89], v[134:137], v[188:191], v[86:89]
	v_mfma_f32_16x16x32_bf16 v[82:85], v[156:159], v[188:191], v[82:85]
	v_mfma_f32_16x16x32_bf16 v[78:81], v[134:137], v[206:209], v[78:81]
	v_mfma_f32_16x16x32_bf16 v[70:73], v[156:159], v[206:209], v[70:73]
	v_mfma_f32_16x16x32_bf16 v[62:65], v[134:137], v[214:217], v[62:65]
	v_mfma_f32_16x16x32_bf16 v[58:61], v[156:159], v[214:217], v[58:61]
	s_setprio 0
	s_setprio 1
	v_mfma_f32_16x16x32_bf16 v[30:33], v[160:163], v[176:179], v[30:33]
	v_mfma_f32_16x16x32_bf16 v[26:29], v[168:171], v[176:179], v[26:29]
	v_mfma_f32_16x16x32_bf16 v[22:25], v[160:163], v[184:187], v[22:25]
	v_mfma_f32_16x16x32_bf16 v[18:21], v[168:171], v[184:187], v[18:21]
	v_mfma_f32_16x16x32_bf16 v[14:17], v[160:163], v[202:205], v[14:17]
	v_mfma_f32_16x16x32_bf16 v[10:13], v[168:171], v[202:205], v[10:13]
	v_mfma_f32_16x16x32_bf16 v[6:9], v[160:163], v[210:213], v[6:9]
	v_mfma_f32_16x16x32_bf16 v[2:5], v[168:171], v[210:213], v[2:5]
	v_mfma_f32_16x16x32_bf16 v[30:33], v[164:167], v[180:183], v[30:33]
	v_mfma_f32_16x16x32_bf16 v[26:29], v[172:175], v[180:183], v[26:29]
	v_mfma_f32_16x16x32_bf16 v[22:25], v[164:167], v[188:191], v[22:25]
	v_mfma_f32_16x16x32_bf16 v[18:21], v[172:175], v[188:191], v[18:21]
	v_mfma_f32_16x16x32_bf16 v[14:17], v[164:167], v[206:209], v[14:17]
	v_mfma_f32_16x16x32_bf16 v[10:13], v[172:175], v[206:209], v[10:13]
	v_mfma_f32_16x16x32_bf16 v[6:9], v[164:167], v[214:217], v[6:9]
	v_mfma_f32_16x16x32_bf16 v[2:5], v[172:175], v[214:217], v[2:5]
	s_setprio 0
	s_barrier
	s_add_i32 s20, s20, 2
	s_add_u32 s43, s43, 0x100
	s_addc_u32 s44, s44, 0
	s_add_u32 s4, s4, 0x100
	s_addc_u32 s5, s5, 0
